# LRU pass1 keeps running chunk aggregate in registers folded into the scan; coalesced two-pass group norm in pass2
# speedup vs baseline: 1.0186x; 1.0186x over previous
.LBB0_290:
	v_add_u32_e32 v5, s6, v0
	ds_read2st64_b32 v[8:9], v5 offset1:1
	ds_read2st64_b32 v[12:13], v6 offset1:1
	ds_read2st64_b32 v[14:15], v6 offset0:2 offset1:3
	s_add_i32 s6, s6, 64
	s_cmpk_lg_i32 s6, 0x100
	s_waitcnt lgkmcnt(2)
	v_add_f32_e32 v7, 0, v8
	v_add_f32_e32 v7, v7, v9
	ds_read2st64_b32 v[8:9], v5 offset0:2 offset1:3
	s_waitcnt lgkmcnt(0)
	v_add_f32_e32 v7, v7, v8
	v_add_f32_e32 v7, v7, v9
	ds_read2st64_b32 v[8:9], v5 offset0:4 offset1:5
	s_waitcnt lgkmcnt(0)
	v_add_f32_e32 v7, v7, v8
	v_add_f32_e32 v7, v7, v9
	ds_read2st64_b32 v[8:9], v5 offset0:6 offset1:7
	s_waitcnt lgkmcnt(0)
	v_add_f32_e32 v5, v7, v8
	v_add_f32_e32 v5, v5, v9
	v_fmamk_f32 v5, v5, 0x3b000000, v190
	v_cmp_gt_f32_e32 vcc, s96, v5
	v_mul_f32_e32 v7, 0x4b800000, v5
	s_nop 0
	v_cndmask_b32_e32 v5, v5, v7, vcc
	v_rsq_f32_e32 v5, v5
	s_nop 0
	v_mul_f32_e32 v7, 0x45800000, v5
	v_cndmask_b32_e32 v8, v5, v7, vcc
	v_ashrrev_i32_e32 v5, 31, v4
	v_lshlrev_b64 v[10:11], 11, v[4:5]
	v_pk_mul_f32 v[12:13], v[12:13], v[8:9] op_sel_hi:[1,0]
	v_pk_mul_f32 v[14:15], v[14:15], v[8:9] op_sel_hi:[1,0]
	v_lshl_add_u64 v[10:11], v[2:3], 0, v[10:11]
	v_cvt_pk_bf16_f32 v12, v12, v13
	v_cvt_pk_bf16_f32 v13, v14, v15
	global_store_dwordx2 v[10:11], v[12:13], off offset:1024
	ds_read2st64_b32 v[12:13], v6 offset0:4 offset1:5
	ds_read2st64_b32 v[14:15], v6 offset0:6 offset1:7
	v_add_u32_e32 v4, 16, v4
	s_waitcnt lgkmcnt(1)
	v_pk_mul_f32 v[12:13], v[12:13], v[8:9] op_sel_hi:[1,0]
	s_waitcnt lgkmcnt(0)
	v_pk_mul_f32 v[14:15], v[8:9], v[14:15] op_sel_hi:[0,1]
	v_cvt_pk_bf16_f32 v12, v12, v13
	v_cvt_pk_bf16_f32 v13, v14, v15
	global_store_dwordx2 v[10:11], v[12:13], off offset:1056
	ds_read2st64_b32 v[12:13], v6 offset0:8 offset1:9
	ds_read2st64_b32 v[14:15], v6 offset0:10 offset1:11
	s_waitcnt lgkmcnt(1)
	v_pk_mul_f32 v[12:13], v[8:9], v[12:13] op_sel_hi:[0,1]
	s_waitcnt lgkmcnt(0)
	v_pk_mul_f32 v[14:15], v[8:9], v[14:15] op_sel_hi:[0,1]
	v_cvt_pk_bf16_f32 v12, v12, v13
	v_cvt_pk_bf16_f32 v13, v14, v15
	global_store_dwordx2 v[10:11], v[12:13], off offset:1088
	ds_read2st64_b32 v[12:13], v6 offset0:12 offset1:13
	ds_read2st64_b32 v[14:15], v6 offset0:14 offset1:15
	v_add_u32_e32 v6, 0x1000, v6
	s_waitcnt lgkmcnt(1)
	v_pk_mul_f32 v[12:13], v[8:9], v[12:13] op_sel_hi:[0,1]
	s_waitcnt lgkmcnt(0)
	v_pk_mul_f32 v[8:9], v[8:9], v[14:15] op_sel_hi:[0,1]
	v_cvt_pk_bf16_f32 v12, v12, v13
	v_cvt_pk_bf16_f32 v13, v8, v9
	global_store_dwordx2 v[10:11], v[12:13], off offset:1120
	s_cbranch_scc1 .LBB0_290
	s_add_i32 s6, s10, s43
	s_ashr_i32 s7, s6, 31
	s_lshl_b64 s[8:9], s[6:7], 10
	v_readlane_b32 s10, v255, 54
	v_lshrrev_b32_e32 v2, 4, v228
	v_and_b32_e32 v3, 15, v228
	s_add_u32 s8, s10, s8
	v_readlane_b32 s10, v255, 55
	v_lshlrev_b32_e32 v3, 4, v3
	s_addc_u32 s9, s10, s9
	s_lshl_b64 s[6:7], s[6:7], 11
	v_lshl_add_u32 v4, v2, 10, v3
	v_lshl_add_u32 v5, v2, 11, v3
	s_add_u32 s6, s33, s6
	s_addc_u32 s7, s42, s7
	v_add_u32_e32 v6, 0x1000, v4
	v_add_u32_e32 v7, 0x2000, v5
	global_load_dwordx4 v[8:11], v4, s[8:9]
	global_load_dwordx4 v[12:15], v4, s[8:9] offset:256
	global_load_dwordx4 v[16:19], v4, s[8:9] offset:512
	global_load_dwordx4 v[20:23], v4, s[8:9] offset:768
	global_load_dwordx4 v[24:27], v6, s[8:9]
	global_load_dwordx4 v[28:31], v6, s[8:9] offset:256
	global_load_dwordx4 v[32:35], v6, s[8:9] offset:512
	global_load_dwordx4 v[36:39], v6, s[8:9] offset:768
	s_mov_b32 s10, 0xffff0000
	s_waitcnt vmcnt(4)
	v_lshlrev_b32_e32 v40, 16, v8
	v_lshlrev_b32_e32 v41, 16, v9
	v_lshlrev_b32_e32 v42, 16, v10
	v_lshlrev_b32_e32 v43, 16, v11
	v_lshlrev_b32_e32 v44, 16, v12
	v_lshlrev_b32_e32 v45, 16, v13
	v_lshlrev_b32_e32 v46, 16, v14
	v_lshlrev_b32_e32 v47, 16, v15
	v_lshlrev_b32_e32 v48, 16, v16
	v_lshlrev_b32_e32 v49, 16, v17
	v_lshlrev_b32_e32 v50, 16, v18
	v_lshlrev_b32_e32 v51, 16, v19
	v_lshlrev_b32_e32 v52, 16, v20
	v_lshlrev_b32_e32 v53, 16, v21
	v_lshlrev_b32_e32 v54, 16, v22
	v_lshlrev_b32_e32 v55, 16, v23
	v_and_b32_e32 v8, s10, v8
	v_and_b32_e32 v9, s10, v9
	v_and_b32_e32 v10, s10, v10
	v_and_b32_e32 v11, s10, v11
	v_and_b32_e32 v12, s10, v12
	v_and_b32_e32 v13, s10, v13
	v_and_b32_e32 v14, s10, v14
	v_and_b32_e32 v15, s10, v15
	v_and_b32_e32 v16, s10, v16
	v_and_b32_e32 v17, s10, v17
	v_and_b32_e32 v18, s10, v18
	v_and_b32_e32 v19, s10, v19
	v_and_b32_e32 v20, s10, v20
	v_and_b32_e32 v21, s10, v21
	v_and_b32_e32 v22, s10, v22
	v_and_b32_e32 v23, s10, v23
	v_mul_f32_e32 v72, v40, v40
	v_mul_f32_e32 v73, v41, v41
	v_mul_f32_e32 v74, v42, v42
	v_mul_f32_e32 v75, v43, v43
	v_fmac_f32_e32 v72, v8, v8
	v_fmac_f32_e32 v73, v9, v9
	v_fmac_f32_e32 v74, v10, v10
	v_fmac_f32_e32 v75, v11, v11
	v_fmac_f32_e32 v72, v44, v44
	v_fmac_f32_e32 v73, v45, v45
	v_fmac_f32_e32 v74, v46, v46
	v_fmac_f32_e32 v75, v47, v47
	v_fmac_f32_e32 v72, v48, v48
	v_fmac_f32_e32 v73, v49, v49
	v_fmac_f32_e32 v74, v50, v50
	v_fmac_f32_e32 v75, v51, v51
	v_fmac_f32_e32 v72, v52, v52
	v_fmac_f32_e32 v73, v53, v53
	v_fmac_f32_e32 v74, v54, v54
	v_fmac_f32_e32 v75, v55, v55
	v_fmac_f32_e32 v72, v12, v12
	v_fmac_f32_e32 v73, v13, v13
	v_fmac_f32_e32 v74, v14, v14
	v_fmac_f32_e32 v75, v15, v15
	v_fmac_f32_e32 v72, v16, v16
	v_fmac_f32_e32 v73, v17, v17
	v_fmac_f32_e32 v74, v18, v18
	v_fmac_f32_e32 v75, v19, v19
	v_fmac_f32_e32 v72, v20, v20
	v_fmac_f32_e32 v73, v21, v21
	v_fmac_f32_e32 v74, v22, v22
	v_fmac_f32_e32 v75, v23, v23
	v_add_f32_e32 v72, v72, v73
	v_add_f32_e32 v74, v74, v75
	s_nop 0
	v_add_f32_e32 v72, v72, v74
	s_waitcnt vmcnt(0)
	v_lshlrev_b32_e32 v56, 16, v24
	v_lshlrev_b32_e32 v57, 16, v25
	v_lshlrev_b32_e32 v58, 16, v26
	v_lshlrev_b32_e32 v59, 16, v27
	v_lshlrev_b32_e32 v60, 16, v28
	v_lshlrev_b32_e32 v61, 16, v29
	v_lshlrev_b32_e32 v62, 16, v30
	v_lshlrev_b32_e32 v63, 16, v31
	v_lshlrev_b32_e32 v64, 16, v32
	v_lshlrev_b32_e32 v65, 16, v33
	v_lshlrev_b32_e32 v66, 16, v34
	v_lshlrev_b32_e32 v67, 16, v35
	v_lshlrev_b32_e32 v68, 16, v36
	v_lshlrev_b32_e32 v69, 16, v37
	v_lshlrev_b32_e32 v70, 16, v38
	v_lshlrev_b32_e32 v71, 16, v39
	v_and_b32_e32 v24, s10, v24
	v_and_b32_e32 v25, s10, v25
	v_and_b32_e32 v26, s10, v26
	v_and_b32_e32 v27, s10, v27
	v_and_b32_e32 v28, s10, v28
	v_and_b32_e32 v29, s10, v29
	v_and_b32_e32 v30, s10, v30
	v_and_b32_e32 v31, s10, v31
	v_and_b32_e32 v32, s10, v32
	v_and_b32_e32 v33, s10, v33
	v_and_b32_e32 v34, s10, v34
	v_and_b32_e32 v35, s10, v35
	v_and_b32_e32 v36, s10, v36
	v_and_b32_e32 v37, s10, v37
	v_and_b32_e32 v38, s10, v38
	v_and_b32_e32 v39, s10, v39
	v_mul_f32_e32 v76, v56, v56
	v_mul_f32_e32 v77, v57, v57
	v_mul_f32_e32 v78, v58, v58
	v_mul_f32_e32 v79, v59, v59
	v_fmac_f32_e32 v76, v24, v24
	v_fmac_f32_e32 v77, v25, v25
	v_fmac_f32_e32 v78, v26, v26
	v_fmac_f32_e32 v79, v27, v27
	v_fmac_f32_e32 v76, v60, v60
	v_fmac_f32_e32 v77, v61, v61
	v_fmac_f32_e32 v78, v62, v62
	v_fmac_f32_e32 v79, v63, v63
	v_fmac_f32_e32 v76, v64, v64
	v_fmac_f32_e32 v77, v65, v65
	v_fmac_f32_e32 v78, v66, v66
	v_fmac_f32_e32 v79, v67, v67
	v_fmac_f32_e32 v76, v68, v68
	v_fmac_f32_e32 v77, v69, v69
	v_fmac_f32_e32 v78, v70, v70
	v_fmac_f32_e32 v79, v71, v71
	v_fmac_f32_e32 v76, v28, v28
	v_fmac_f32_e32 v77, v29, v29
	v_fmac_f32_e32 v78, v30, v30
	v_fmac_f32_e32 v79, v31, v31
	v_fmac_f32_e32 v76, v32, v32
	v_fmac_f32_e32 v77, v33, v33
	v_fmac_f32_e32 v78, v34, v34
	v_fmac_f32_e32 v79, v35, v35
	v_fmac_f32_e32 v76, v36, v36
	v_fmac_f32_e32 v77, v37, v37
	v_fmac_f32_e32 v78, v38, v38
	v_fmac_f32_e32 v79, v39, v39
	v_add_f32_e32 v76, v76, v77
	v_add_f32_e32 v78, v78, v79
	s_nop 0
	v_add_f32_e32 v76, v76, v78
	s_nop 1
	v_add_f32_dpp v73, v72, v72 quad_perm:[1,0,3,2] row_mask:0xf bank_mask:0xf
	v_add_f32_dpp v77, v76, v76 quad_perm:[1,0,3,2] row_mask:0xf bank_mask:0xf
	s_nop 0
	v_add_f32_dpp v72, v73, v73 quad_perm:[2,3,0,1] row_mask:0xf bank_mask:0xf
	v_add_f32_dpp v76, v77, v77 quad_perm:[2,3,0,1] row_mask:0xf bank_mask:0xf
	s_nop 0
	v_add_f32_dpp v73, v72, v72 row_half_mirror row_mask:0xf bank_mask:0xf
	v_add_f32_dpp v77, v76, v76 row_half_mirror row_mask:0xf bank_mask:0xf
	s_nop 0
	v_add_f32_dpp v72, v73, v73 row_mirror row_mask:0xf bank_mask:0xf
	v_add_f32_dpp v76, v77, v77 row_mirror row_mask:0xf bank_mask:0xf
	s_nop 0
	v_fmamk_f32 v72, v72, 0x3b000000, v190
	v_fmamk_f32 v76, v76, 0x3b000000, v190
	v_cmp_gt_f32_e32 vcc, s96, v72
	v_cmp_gt_f32_e64 s[8:9], s96, v76
	v_mul_f32_e32 v73, 0x4b800000, v72
	v_mul_f32_e32 v77, 0x4b800000, v76
	v_cndmask_b32_e32 v72, v72, v73, vcc
	v_cndmask_b32_e64 v76, v76, v77, s[8:9]
	v_rsq_f32_e32 v72, v72
	v_rsq_f32_e32 v76, v76
	s_nop 0
	v_mul_f32_e32 v73, 0x45800000, v72
	v_mul_f32_e32 v77, 0x45800000, v76
	v_cndmask_b32_e32 v72, v72, v73, vcc
	v_cndmask_b32_e64 v76, v76, v77, s[8:9]
	v_mul_f32_e32 v40, v72, v40
	v_mul_f32_e32 v41, v72, v41
	v_mul_f32_e32 v42, v72, v42
	v_mul_f32_e32 v43, v72, v43
	v_mul_f32_e32 v44, v72, v44
	v_mul_f32_e32 v45, v72, v45
	v_mul_f32_e32 v46, v72, v46
	v_mul_f32_e32 v47, v72, v47
	v_mul_f32_e32 v48, v72, v48
	v_mul_f32_e32 v49, v72, v49
	v_mul_f32_e32 v50, v72, v50
	v_mul_f32_e32 v51, v72, v51
	v_mul_f32_e32 v52, v72, v52
	v_mul_f32_e32 v53, v72, v53
	v_mul_f32_e32 v54, v72, v54
	v_mul_f32_e32 v55, v72, v55
	v_mul_f32_e32 v8, v72, v8
	v_mul_f32_e32 v9, v72, v9
	v_mul_f32_e32 v10, v72, v10
	v_mul_f32_e32 v11, v72, v11
	v_mul_f32_e32 v12, v72, v12
	v_mul_f32_e32 v13, v72, v13
	v_mul_f32_e32 v14, v72, v14
	v_mul_f32_e32 v15, v72, v15
	v_mul_f32_e32 v16, v72, v16
	v_mul_f32_e32 v17, v72, v17
	v_mul_f32_e32 v18, v72, v18
	v_mul_f32_e32 v19, v72, v19
	v_mul_f32_e32 v20, v72, v20
	v_mul_f32_e32 v21, v72, v21
	v_mul_f32_e32 v22, v72, v22
	v_mul_f32_e32 v23, v72, v23
	v_cvt_pk_bf16_f32 v8, v40, v8
	v_cvt_pk_bf16_f32 v9, v41, v9
	v_cvt_pk_bf16_f32 v10, v42, v10
	v_cvt_pk_bf16_f32 v11, v43, v11
	v_cvt_pk_bf16_f32 v12, v44, v12
	v_cvt_pk_bf16_f32 v13, v45, v13
	v_cvt_pk_bf16_f32 v14, v46, v14
	v_cvt_pk_bf16_f32 v15, v47, v15
	v_cvt_pk_bf16_f32 v16, v48, v16
	v_cvt_pk_bf16_f32 v17, v49, v17
	v_cvt_pk_bf16_f32 v18, v50, v18
	v_cvt_pk_bf16_f32 v19, v51, v19
	v_cvt_pk_bf16_f32 v20, v52, v20
	v_cvt_pk_bf16_f32 v21, v53, v21
	v_cvt_pk_bf16_f32 v22, v54, v22
	v_cvt_pk_bf16_f32 v23, v55, v23
	v_mul_f32_e32 v56, v76, v56
	v_mul_f32_e32 v57, v76, v57
	v_mul_f32_e32 v58, v76, v58
	v_mul_f32_e32 v59, v76, v59
	v_mul_f32_e32 v60, v76, v60
	v_mul_f32_e32 v61, v76, v61
	v_mul_f32_e32 v62, v76, v62
	v_mul_f32_e32 v63, v76, v63
	v_mul_f32_e32 v64, v76, v64
	v_mul_f32_e32 v65, v76, v65
	v_mul_f32_e32 v66, v76, v66
	v_mul_f32_e32 v67, v76, v67
	v_mul_f32_e32 v68, v76, v68
	v_mul_f32_e32 v69, v76, v69
	v_mul_f32_e32 v70, v76, v70
	v_mul_f32_e32 v71, v76, v71
	v_mul_f32_e32 v24, v76, v24
	v_mul_f32_e32 v25, v76, v25
	v_mul_f32_e32 v26, v76, v26
	v_mul_f32_e32 v27, v76, v27
	v_mul_f32_e32 v28, v76, v28
	v_mul_f32_e32 v29, v76, v29
	v_mul_f32_e32 v30, v76, v30
	v_mul_f32_e32 v31, v76, v31
	v_mul_f32_e32 v32, v76, v32
	v_mul_f32_e32 v33, v76, v33
	v_mul_f32_e32 v34, v76, v34
	v_mul_f32_e32 v35, v76, v35
	v_mul_f32_e32 v36, v76, v36
	v_mul_f32_e32 v37, v76, v37
	v_mul_f32_e32 v38, v76, v38
	v_mul_f32_e32 v39, v76, v39
	v_cvt_pk_bf16_f32 v24, v56, v24
	v_cvt_pk_bf16_f32 v25, v57, v25
	v_cvt_pk_bf16_f32 v26, v58, v26
	v_cvt_pk_bf16_f32 v27, v59, v27
	v_cvt_pk_bf16_f32 v28, v60, v28
	v_cvt_pk_bf16_f32 v29, v61, v29
	v_cvt_pk_bf16_f32 v30, v62, v30
	v_cvt_pk_bf16_f32 v31, v63, v31
	v_cvt_pk_bf16_f32 v32, v64, v32
	v_cvt_pk_bf16_f32 v33, v65, v33
	v_cvt_pk_bf16_f32 v34, v66, v34
	v_cvt_pk_bf16_f32 v35, v67, v35
	v_cvt_pk_bf16_f32 v36, v68, v36
	v_cvt_pk_bf16_f32 v37, v69, v37
	v_cvt_pk_bf16_f32 v38, v70, v38
	v_cvt_pk_bf16_f32 v39, v71, v39
	global_store_dwordx4 v5, v[8:11], s[6:7]
	global_store_dwordx4 v5, v[12:15], s[6:7] offset:256
	global_store_dwordx4 v5, v[16:19], s[6:7] offset:512
	global_store_dwordx4 v5, v[20:23], s[6:7] offset:768
	global_store_dwordx4 v7, v[24:27], s[6:7]
	global_store_dwordx4 v7, v[28:31], s[6:7] offset:256
	global_store_dwordx4 v7, v[32:35], s[6:7] offset:512
	global_store_dwordx4 v7, v[36:39], s[6:7] offset:768
	s_waitcnt lgkmcnt(0)
	s_add_i32 s57, s57, s81
	v_readlane_b32 s6, v255, 31
	s_cmp_ge_i32 s57, s6
	s_barrier
	s_cbranch_scc0 .LBB0_268

.LBB0_337:
	s_and_b32 s43, s58, 1
	s_and_b64 s[8:9], s[8:9], exec
	s_cselect_b32 s33, s3, s11
	s_movk_i32 s3, 0x1000
	s_cselect_b32 s3, 0x100, s3
	s_ashr_i32 s11, s10, 31
	s_lshl_b64 s[8:9], s[10:11], 10
	s_ashr_i32 s10, s10, 4
	s_ashr_i32 s11, s10, 31
	s_lshl_b64 s[10:11], s[10:11], 15
	s_add_u32 s12, s4, s8
	v_and_b32_e32 v184, 15, v2
	v_ashrrev_i32_e32 v3, 4, v2
	s_addc_u32 s13, s5, s9
	s_lshl_b32 s8, s43, 17
	s_add_u32 s8, s78, s8
	s_waitcnt vmcnt(5)
	v_lshlrev_b32_e32 v16, 6, v184
	v_lshlrev_b32_e32 v4, 3, v3
	s_addc_u32 s9, s42, 0
	v_add_u32_e32 v6, v16, v4
	s_add_u32 s14, s8, 0x10000
	v_ashrrev_i32_e32 v7, 31, v6
	s_addc_u32 s15, s9, 0
	v_lshlrev_b64 v[8:9], 1, v[6:7]
	v_add_u32_e32 v12, 32, v6
	v_lshl_add_u64 v[10:11], s[8:9], 0, v[8:9]
	v_lshl_add_u64 v[8:9], s[14:15], 0, v[8:9]
	v_ashrrev_i32_e32 v13, 31, v12
	global_load_dwordx4 v[34:37], v[10:11], off
	global_load_dwordx4 v[38:41], v[10:11], off offset:64
	v_lshl_add_u64 v[12:13], v[12:13], 1, s[14:15]
	global_load_dwordx4 v[42:45], v[8:9], off
	global_load_dwordx4 v[46:49], v[12:13], off
	v_add_u32_e32 v8, 0x400, v6
	v_ashrrev_i32_e32 v9, 31, v8
	v_add_u32_e32 v12, 0x420, v6
	v_lshl_add_u64 v[8:9], v[8:9], 1, s[14:15]
	v_ashrrev_i32_e32 v13, 31, v12
	global_load_dwordx4 v[50:53], v[10:11], off offset:2048
	global_load_dwordx4 v[54:57], v[10:11], off offset:2112
	v_lshl_add_u64 v[10:11], v[12:13], 1, s[14:15]
	global_load_dwordx4 v[58:61], v[8:9], off
	global_load_dwordx4 v[62:65], v[10:11], off
	v_add_u32_e32 v8, 0x800, v6
	v_ashrrev_i32_e32 v9, 31, v8
	v_lshlrev_b64 v[8:9], 1, v[8:9]
	v_lshl_add_u64 v[10:11], s[8:9], 0, v[8:9]
	v_lshl_add_u64 v[8:9], s[14:15], 0, v[8:9]
	global_load_dwordx4 v[66:69], v[10:11], off
	global_load_dwordx4 v[70:73], v[8:9], off
	v_add_u32_e32 v8, 0x820, v6
	v_ashrrev_i32_e32 v9, 31, v8
	v_lshlrev_b64 v[8:9], 1, v[8:9]
	v_lshl_add_u64 v[10:11], s[8:9], 0, v[8:9]
	v_lshl_add_u64 v[8:9], s[14:15], 0, v[8:9]
	global_load_dwordx4 v[74:77], v[10:11], off
	global_load_dwordx4 v[78:81], v[8:9], off
	v_add_u32_e32 v8, 0xc00, v6
	v_ashrrev_i32_e32 v9, 31, v8
	v_add_u32_e32 v6, 0xc20, v6
	v_lshlrev_b64 v[8:9], 1, v[8:9]
	v_ashrrev_i32_e32 v7, 31, v6
	v_or_b32_e32 v186, s33, v184
	v_lshl_add_u64 v[10:11], s[8:9], 0, v[8:9]
	v_lshl_add_u64 v[8:9], s[14:15], 0, v[8:9]
	v_lshlrev_b64 v[6:7], 1, v[6:7]
	v_add_u32_e32 v5, -2, v186
	global_load_dwordx4 v[82:85], v[10:11], off
	global_load_dwordx4 v[86:89], v[8:9], off
	v_lshl_add_u64 v[8:9], s[8:9], 0, v[6:7]
	v_cmp_lt_i32_e32 vcc, 1, v186
	v_cmp_gt_i32_e64 s[8:9], s3, v5
	v_lshl_add_u64 v[6:7], s[14:15], 0, v[6:7]
	v_add_u32_e32 v0, -2, v184
	s_and_b64 vcc, vcc, s[8:9]
	global_load_dwordx4 v[90:93], v[8:9], off
	global_load_dwordx4 v[94:97], v[6:7], off
	v_cndmask_b32_e32 v6, v184, v0, vcc
	v_cmp_lt_i32_e32 vcc, 0, v186
	v_cmp_ge_i32_e64 s[8:9], s3, v186
	v_ashrrev_i32_e32 v5, 31, v4
	s_and_b64 vcc, vcc, s[8:9]
	v_lshlrev_b64 v[8:9], 1, v[4:5]
	v_add_u32_e32 v5, 1, v186
	v_subbrev_co_u32_e32 v10, vcc, 0, v184, vcc
	v_cmp_lt_i32_e32 vcc, -2, v186
	v_cmp_gt_i32_e64 s[8:9], s3, v5
	v_ashrrev_i32_e32 v7, 31, v6
	v_lshlrev_b32_e32 v0, 10, v184
	s_and_b64 vcc, vcc, s[8:9]
	v_lshlrev_b64 v[6:7], 10, v[6:7]
	v_ashrrev_i32_e32 v11, 31, v10
	v_lshl_add_u64 v[12:13], s[12:13], 0, v[0:1]
	v_addc_co_u32_e32 v0, vcc, 0, v184, vcc
	v_lshl_add_u64 v[6:7], s[12:13], 0, v[6:7]
	v_lshlrev_b64 v[10:11], 10, v[10:11]
	v_lshlrev_b32_e32 v0, 10, v0
	v_lshl_add_u64 v[6:7], v[6:7], 0, v[8:9]
	v_lshl_add_u64 v[10:11], s[12:13], 0, v[10:11]
	v_lshl_add_u64 v[14:15], s[12:13], 0, v[0:1]
	v_lshl_add_u64 v[10:11], v[10:11], 0, v[8:9]
	v_lshl_add_u64 v[12:13], v[12:13], 0, v[8:9]
	v_lshl_add_u64 v[14:15], v[14:15], 0, v[8:9]
	global_load_dwordx4 v[126:129], v[6:7], off
	global_load_dwordx4 v[110:113], v[6:7], off offset:64
	global_load_dwordx4 v[122:125], v[10:11], off
	global_load_dwordx4 v[106:109], v[10:11], off offset:64
	global_load_dwordx4 v[118:121], v[12:13], off
	global_load_dwordx4 v[102:105], v[12:13], off offset:64
	global_load_dwordx4 v[114:117], v[14:15], off
	global_load_dwordx4 v[98:101], v[14:15], off offset:64
	v_add_lshl_u32 v4, v4, s18, 2
	v_readlane_b32 s9, v254, 51
	v_readlane_b32 s8, v254, 50
	s_mov_b32 s37, 0
	v_add_u32_e32 v187, s9, v4
	v_add_u32_e32 v188, s8, v4
	s_or_b32 s48, s3, 2
	v_add_u32_e32 v4, 0x80, v4
	s_mov_b32 s38, s36
	s_mov_b32 s39, s37
	v_mov_b64_e32 v[10:11], s[36:37]
	s_cmp_gt_i32 s33, -1
	v_add_u32_e32 v189, s9, v4
	v_add_u32_e32 v196, s8, v4
	v_mov_b32_e32 v4, s77
	s_movk_i32 s8, 0x110
	v_mov_b64_e32 v[12:13], s[38:39]
	s_cselect_b64 s[38:39], -1, 0
	v_mad_u32_u24 v4, v184, s8, v4
	s_lshl_b32 s8, s43, 9
	s_add_i32 s49, s3, -1
	s_add_i32 s8, s8, s18
	v_lshlrev_b32_e32 v138, 2, v3
	s_cmp_eq_u32 s43, 0
	v_and_b32_e32 v0, 48, v2
	v_and_b32_e32 v7, -16, v2
	v_add_lshl_u32 v2, s8, v138, 2
	s_cselect_b64 s[8:9], -1, 0
	s_cmp_eq_u32 s43, 1
	v_lshl_add_u64 v[140:141], s[12:13], 0, v[8:9]
	s_mul_i32 s12, s43, 0x2200000
	v_lshl_add_u32 v185, v3, 7, s76
	v_lshlrev_b32_e32 v6, 5, v3
	v_add_u32_e32 v3, 64, v2
	s_cselect_b64 s[44:45], -1, 0
	s_add_u32 s10, s12, s10
	v_add_u32_e32 v197, s41, v2
	v_add_u32_e32 v198, s68, v2
	v_add_u32_e32 v199, s69, v2
	v_add_u32_e32 v202, s41, v3
	v_add_u32_e32 v203, s68, v3
	v_add_u32_e32 v204, s69, v3
	v_add_u32_e32 v3, 0x80, v2
	v_add_u32_e32 v2, 0xc0, v2
	s_addc_u32 s11, 0, s11
	v_ashrrev_i32_e32 v139, 31, v138
	v_add_u32_e32 v205, s41, v3
	v_add_u32_e32 v206, s68, v3
	v_add_u32_e32 v207, s69, v3
	v_add_u32_e32 v208, s41, v2
	v_add_u32_e32 v209, s68, v2
	v_add_u32_e32 v210, s69, v2
	v_or_b32_e32 v2, s10, v16
	v_mov_b32_e32 v3, s11
	v_or_b32_e32 v5, 15, v0
	v_lshl_add_u64 v[2:3], v[138:139], 2, v[2:3]
	v_cndmask_b32_e64 v211, v0, v5, s[8:9]
	v_lshl_add_u64 v[142:143], s[24:25], 0, v[2:3]
	v_add_u32_e32 v212, v4, v6
	v_add_u32_e32 v213, v4, v7
	v_mov_b32_e32 v172, 1.0
	v_mov_b32_e32 v173, 1.0
	v_mov_b32_e32 v174, 1.0
	v_mov_b32_e32 v175, 1.0
	v_mov_b32_e32 v176, 1.0
	v_mov_b32_e32 v177, 1.0
	v_mov_b32_e32 v178, 1.0
	v_mov_b32_e32 v179, 1.0
	v_mov_b32_e32 v180, 1.0
	v_mov_b32_e32 v181, 1.0
	v_mov_b32_e32 v182, 1.0
	v_mov_b32_e32 v183, 1.0
	v_mov_b32_e32 v192, 1.0
	v_mov_b32_e32 v193, 1.0
	v_mov_b32_e32 v194, 1.0
	v_mov_b32_e32 v195, 1.0
	v_mov_b32_e32 v214, 0
	v_mov_b32_e32 v215, 0
	v_mov_b32_e32 v216, 0
	v_mov_b32_e32 v217, 0
	v_mov_b32_e32 v218, 0
	v_mov_b32_e32 v219, 0
	v_mov_b32_e32 v220, 0
	v_mov_b32_e32 v221, 0
	v_mov_b32_e32 v222, 0
	v_mov_b32_e32 v223, 0
	v_mov_b32_e32 v224, 0
	v_mov_b32_e32 v225, 0
	v_mov_b32_e32 v234, 0
	v_mov_b32_e32 v235, 0
	v_mov_b32_e32 v236, 0
	v_mov_b32_e32 v237, 0
	s_branch .LBB0_339
.LBB0_338:
	v_lshl_add_u64 v[142:143], v[142:143], 0, s[88:89]
	s_cmp_eq_u32 s37, 64
	s_cbranch_scc1 .LBB0_343
.LBB0_339:
	ds_read_b128 v[2:5], v187
	ds_read_b128 v[6:9], v187 offset:16
	ds_read_b128 v[10:13], v188
	ds_read_b128 v[14:17], v188 offset:16
	s_mov_b32 s40, s37
	v_add_u32_e32 v0, s40, v186
	v_cmp_lt_i32_e32 vcc, 1, v0
	v_cmp_gt_i32_e64 s[10:11], s48, v0
	s_and_b64 s[14:15], vcc, s[10:11]
	s_waitcnt lgkmcnt(1)
	v_cndmask_b32_e64 v27, 0, v13, s[14:15]
	v_cndmask_b32_e64 v26, 0, v12, s[14:15]
	v_cndmask_b32_e64 v29, 0, v11, s[14:15]
	v_cndmask_b32_e64 v28, 0, v10, s[14:15]
	s_waitcnt lgkmcnt(0)
	v_cndmask_b32_e64 v11, 0, v17, s[14:15]
	v_cndmask_b32_e64 v10, 0, v16, s[14:15]
	v_cndmask_b32_e64 v13, 0, v15, s[14:15]
	v_cndmask_b32_e64 v12, 0, v14, s[14:15]
	ds_read_b128 v[14:17], v188 offset:2048
	v_cmp_lt_i32_e32 vcc, 0, v0
	v_cmp_ge_i32_e64 s[10:11], s3, v0
	s_and_b64 s[10:11], vcc, s[10:11]
	v_cmp_gt_i32_e32 vcc, s3, v0
	s_waitcnt vmcnt(27) lgkmcnt(0)
	v_cndmask_b32_e64 v31, 0, v17, s[10:11]
	v_cndmask_b32_e64 v30, 0, v16, s[10:11]
	ds_read_b128 v[16:19], v188 offset:2064
	v_cndmask_b32_e64 v33, 0, v15, s[10:11]
	v_cndmask_b32_e64 v32, 0, v14, s[10:11]
	s_and_b64 s[12:13], s[38:39], vcc
	s_waitcnt vmcnt(7)
	v_lshlrev_b32_e32 v134, 16, v126
	s_waitcnt lgkmcnt(0)
	v_cndmask_b32_e64 v15, 0, v19, s[10:11]
	v_cndmask_b32_e64 v14, 0, v18, s[10:11]
	ds_read_b128 v[18:21], v188 offset:4096
	v_and_b32_e32 v135, 0xffff0000, v126
	v_cmp_lt_i32_e32 vcc, -2, v0
	v_cmp_gt_i32_e64 s[16:17], s49, v0
	v_pk_fma_f32 v[2:3], v[28:29], v[134:135], v[2:3]
	s_waitcnt lgkmcnt(0)
	v_cndmask_b32_e64 v131, 0, v21, s[12:13]
	v_cndmask_b32_e64 v130, 0, v20, s[12:13]
	ds_read_b128 v[20:23], v188 offset:4112
	v_cndmask_b32_e64 v133, 0, v19, s[12:13]
	v_cndmask_b32_e64 v132, 0, v18, s[12:13]
	s_waitcnt vmcnt(5)
	v_lshlrev_b32_e32 v28, 16, v122
	v_and_b32_e32 v29, 0xffff0000, v122
	s_waitcnt lgkmcnt(0)
	v_cndmask_b32_e64 v19, 0, v23, s[12:13]
	v_cndmask_b32_e64 v18, 0, v22, s[12:13]
	ds_read_b128 v[22:25], v188 offset:6144
	s_and_b64 vcc, vcc, s[16:17]
	v_pk_fma_f32 v[2:3], v[32:33], v[28:29], v[2:3]
	s_waitcnt vmcnt(3)
	v_lshlrev_b32_e32 v28, 16, v118
	v_and_b32_e32 v29, 0xffff0000, v118
	s_waitcnt lgkmcnt(0)
	v_cndmask_b32_e32 v23, 0, v23, vcc
	v_cndmask_b32_e32 v22, 0, v22, vcc
	v_pk_fma_f32 v[2:3], v[132:133], v[28:29], v[2:3]
	s_waitcnt vmcnt(1)
	v_lshlrev_b32_e32 v28, 16, v114
	v_and_b32_e32 v29, 0xffff0000, v114
	v_pk_fma_f32 v[2:3], v[22:23], v[28:29], v[2:3]
	v_lshlrev_b32_e32 v22, 16, v127
	v_and_b32_e32 v23, 0xffff0000, v127
	v_pk_fma_f32 v[4:5], v[26:27], v[22:23], v[4:5]
	v_lshlrev_b32_e32 v22, 16, v123
	v_and_b32_e32 v23, 0xffff0000, v123
	v_pk_fma_f32 v[4:5], v[30:31], v[22:23], v[4:5]
	v_lshlrev_b32_e32 v22, 16, v119
	v_and_b32_e32 v23, 0xffff0000, v119
	v_cndmask_b32_e32 v25, 0, v25, vcc
	v_cndmask_b32_e32 v24, 0, v24, vcc
	v_pk_fma_f32 v[4:5], v[130:131], v[22:23], v[4:5]
	v_lshlrev_b32_e32 v22, 16, v115
	v_and_b32_e32 v23, 0xffff0000, v115
	v_pk_fma_f32 v[4:5], v[24:25], v[22:23], v[4:5]
	ds_read_b128 v[22:25], v188 offset:6160
	v_lshlrev_b32_e32 v26, 16, v128
	v_and_b32_e32 v27, 0xffff0000, v128
	v_cndmask_b32_e64 v17, 0, v17, s[10:11]
	v_cndmask_b32_e64 v16, 0, v16, s[10:11]
	v_pk_fma_f32 v[6:7], v[12:13], v[26:27], v[6:7]
	v_lshlrev_b32_e32 v12, 16, v124
	v_and_b32_e32 v13, 0xffff0000, v124
	v_cndmask_b32_e64 v21, 0, v21, s[12:13]
	v_cndmask_b32_e64 v20, 0, v20, s[12:13]
	v_pk_fma_f32 v[6:7], v[16:17], v[12:13], v[6:7]
	v_lshlrev_b32_e32 v12, 16, v120
	v_and_b32_e32 v13, 0xffff0000, v120
	s_waitcnt lgkmcnt(0)
	v_cndmask_b32_e32 v23, 0, v23, vcc
	v_cndmask_b32_e32 v22, 0, v22, vcc
	v_pk_fma_f32 v[6:7], v[20:21], v[12:13], v[6:7]
	v_lshlrev_b32_e32 v12, 16, v116
	v_and_b32_e32 v13, 0xffff0000, v116
	v_pk_fma_f32 v[6:7], v[22:23], v[12:13], v[6:7]
	v_lshlrev_b32_e32 v12, 16, v129
	v_and_b32_e32 v13, 0xffff0000, v129
	v_pk_fma_f32 v[8:9], v[10:11], v[12:13], v[8:9]
	v_lshlrev_b32_e32 v10, 16, v125
	v_and_b32_e32 v11, 0xffff0000, v125
	v_pk_fma_f32 v[8:9], v[14:15], v[10:11], v[8:9]
	v_lshlrev_b32_e32 v10, 16, v121
	v_and_b32_e32 v11, 0xffff0000, v121
	v_cndmask_b32_e32 v25, 0, v25, vcc
	v_cndmask_b32_e32 v24, 0, v24, vcc
	v_pk_fma_f32 v[8:9], v[18:19], v[10:11], v[8:9]
	v_lshlrev_b32_e32 v10, 16, v117
	v_and_b32_e32 v11, 0xffff0000, v117
	v_pk_fma_f32 v[8:9], v[24:25], v[10:11], v[8:9]
	ds_read_b128 v[14:17], v189
	ds_read_b128 v[10:13], v189 offset:16
	ds_read_b128 v[18:21], v196
	ds_read_b128 v[22:25], v196 offset:16
	v_lshlrev_b32_e32 v126, 16, v110
	v_and_b32_e32 v127, 0xffff0000, v110
	v_cvt_pk_bf16_f32 v134, v2, v3
	s_waitcnt lgkmcnt(1)
	v_cndmask_b32_e64 v115, 0, v21, s[14:15]
	v_cndmask_b32_e64 v114, 0, v20, s[14:15]
	v_cndmask_b32_e64 v117, 0, v19, s[14:15]
	v_cndmask_b32_e64 v116, 0, v18, s[14:15]
	s_waitcnt lgkmcnt(0)
	v_cndmask_b32_e64 v19, 0, v25, s[14:15]
	v_cndmask_b32_e64 v18, 0, v24, s[14:15]
	v_cndmask_b32_e64 v21, 0, v23, s[14:15]
	v_cndmask_b32_e64 v20, 0, v22, s[14:15]
	ds_read_b128 v[22:25], v196 offset:2048
	v_pk_fma_f32 v[14:15], v[116:117], v[126:127], v[14:15]
	v_lshlrev_b32_e32 v116, 16, v106
	v_and_b32_e32 v117, 0xffff0000, v106
	v_cvt_pk_bf16_f32 v135, v4, v5
	s_waitcnt lgkmcnt(0)
	v_cndmask_b32_e64 v119, 0, v25, s[10:11]
	v_cndmask_b32_e64 v118, 0, v24, s[10:11]
	ds_read_b128 v[24:27], v196 offset:2064
	v_cndmask_b32_e64 v121, 0, v23, s[10:11]
	v_cndmask_b32_e64 v120, 0, v22, s[10:11]
	v_pk_fma_f32 v[14:15], v[120:121], v[116:117], v[14:15]
	v_lshlrev_b32_e32 v116, 16, v102
	s_waitcnt lgkmcnt(0)
	v_cndmask_b32_e64 v23, 0, v27, s[10:11]
	v_cndmask_b32_e64 v22, 0, v26, s[10:11]
	ds_read_b128 v[26:29], v196 offset:4096
	v_and_b32_e32 v117, 0xffff0000, v102
	v_cndmask_b32_e64 v25, 0, v25, s[10:11]
	v_cndmask_b32_e64 v24, 0, v24, s[10:11]
	v_cvt_pk_bf16_f32 v136, v6, v7
	s_waitcnt lgkmcnt(0)
	v_cndmask_b32_e64 v123, 0, v29, s[12:13]
	v_cndmask_b32_e64 v122, 0, v28, s[12:13]
	ds_read_b128 v[28:31], v196 offset:4112
	v_cndmask_b32_e64 v125, 0, v27, s[12:13]
	v_cndmask_b32_e64 v124, 0, v26, s[12:13]
	v_pk_fma_f32 v[14:15], v[124:125], v[116:117], v[14:15]
	s_waitcnt vmcnt(0)
	v_lshlrev_b32_e32 v116, 16, v98
	s_waitcnt lgkmcnt(0)
	v_cndmask_b32_e64 v27, 0, v31, s[12:13]
	v_cndmask_b32_e64 v26, 0, v30, s[12:13]
	ds_read_b128 v[30:33], v196 offset:6144
	v_and_b32_e32 v117, 0xffff0000, v98
	v_lshlrev_b32_e32 v98, 16, v112
	v_cndmask_b32_e64 v29, 0, v29, s[12:13]
	v_cndmask_b32_e64 v28, 0, v28, s[12:13]
	s_waitcnt lgkmcnt(0)
	v_cndmask_b32_e32 v31, 0, v31, vcc
	v_cndmask_b32_e32 v30, 0, v30, vcc
	v_pk_fma_f32 v[14:15], v[30:31], v[116:117], v[14:15]
	v_lshlrev_b32_e32 v30, 16, v111
	v_and_b32_e32 v31, 0xffff0000, v111
	v_pk_fma_f32 v[16:17], v[114:115], v[30:31], v[16:17]
	v_lshlrev_b32_e32 v30, 16, v107
	v_and_b32_e32 v31, 0xffff0000, v107
	v_pk_fma_f32 v[16:17], v[118:119], v[30:31], v[16:17]
	v_lshlrev_b32_e32 v30, 16, v103
	v_and_b32_e32 v31, 0xffff0000, v103
	v_cndmask_b32_e32 v33, 0, v33, vcc
	v_cndmask_b32_e32 v32, 0, v32, vcc
	v_pk_fma_f32 v[16:17], v[122:123], v[30:31], v[16:17]
	v_lshlrev_b32_e32 v30, 16, v99
	v_and_b32_e32 v31, 0xffff0000, v99
	v_pk_fma_f32 v[16:17], v[32:33], v[30:31], v[16:17]
	ds_read_b128 v[30:33], v196 offset:6160
	v_and_b32_e32 v99, 0xffff0000, v112
	v_pk_fma_f32 v[10:11], v[20:21], v[98:99], v[10:11]
	v_lshlrev_b32_e32 v20, 16, v108
	v_and_b32_e32 v21, 0xffff0000, v108
	v_pk_fma_f32 v[10:11], v[24:25], v[20:21], v[10:11]
	v_lshlrev_b32_e32 v20, 16, v104
	v_and_b32_e32 v21, 0xffff0000, v104
	s_waitcnt lgkmcnt(0)
	v_cndmask_b32_e32 v31, 0, v31, vcc
	v_cndmask_b32_e32 v30, 0, v30, vcc
	v_pk_fma_f32 v[10:11], v[28:29], v[20:21], v[10:11]
	v_lshlrev_b32_e32 v20, 16, v100
	v_and_b32_e32 v21, 0xffff0000, v100
	v_pk_fma_f32 v[10:11], v[30:31], v[20:21], v[10:11]
	v_lshlrev_b32_e32 v20, 16, v113
	v_and_b32_e32 v21, 0xffff0000, v113
	v_pk_fma_f32 v[12:13], v[18:19], v[20:21], v[12:13]
	v_lshlrev_b32_e32 v18, 16, v109
	v_and_b32_e32 v19, 0xffff0000, v109
	v_pk_fma_f32 v[12:13], v[22:23], v[18:19], v[12:13]
	v_lshlrev_b32_e32 v18, 16, v105
	v_and_b32_e32 v19, 0xffff0000, v105
	v_cndmask_b32_e32 v33, 0, v33, vcc
	v_cndmask_b32_e32 v32, 0, v32, vcc
	v_pk_fma_f32 v[12:13], v[26:27], v[18:19], v[12:13]
	v_lshlrev_b32_e32 v18, 16, v101
	v_and_b32_e32 v19, 0xffff0000, v101
	v_pk_fma_f32 v[12:13], v[32:33], v[18:19], v[12:13]
	ds_write_b128 v212, v[2:5]
	ds_write_b128 v212, v[6:9] offset:16
	ds_write_b128 v212, v[14:17] offset:128
	ds_write_b128 v212, v[10:13] offset:144
	s_waitcnt lgkmcnt(0)
	v_cvt_pk_bf16_f32 v6, v14, v15
	v_cvt_pk_bf16_f32 v7, v16, v17
	ds_read_b128 v[150:153], v213
	ds_read_b128 v[26:29], v213 offset:64
	ds_read_b128 v[14:17], v213 offset:128
	ds_read_b128 v[2:5], v213 offset:192
	s_waitcnt lgkmcnt(0)
	v_cvt_pk_bf16_f32 v137, v8, v9
	v_cvt_pk_bf16_f32 v8, v10, v11
	v_cvt_pk_bf16_f32 v9, v12, v13
	s_add_i32 s37, s37, 16
	s_cmp_lg_u32 s40, 48
	s_cselect_b32 s10, s37, 48
	v_or_b32_e32 v20, s10, v184
	v_add_u32_e32 v21, s33, v20
	v_cmp_lt_i32_e32 vcc, 1, v21
	v_cmp_gt_i32_e64 s[10:11], s48, v21
	v_add_u32_e32 v0, -2, v20
	s_and_b64 vcc, vcc, s[10:11]
	v_cndmask_b32_e32 v10, v20, v0, vcc
	v_cmp_lt_i32_e32 vcc, 0, v21
	v_cmp_ge_i32_e64 s[10:11], s3, v21
	s_and_b64 vcc, vcc, s[10:11]
	v_subbrev_co_u32_e32 v12, vcc, 0, v20, vcc
	v_cmp_lt_i32_e32 vcc, -2, v21
	v_cmp_gt_i32_e64 s[10:11], s49, v21
	v_ashrrev_i32_e32 v11, 31, v10
	v_lshlrev_b32_e32 v0, 10, v20
	s_and_b64 vcc, vcc, s[10:11]
	v_lshlrev_b64 v[10:11], 10, v[10:11]
	v_ashrrev_i32_e32 v13, 31, v12
	v_lshl_add_u64 v[18:19], v[140:141], 0, v[0:1]
	v_addc_co_u32_e32 v0, vcc, 0, v20, vcc
	v_lshl_add_u64 v[10:11], v[140:141], 0, v[10:11]
	v_lshlrev_b64 v[12:13], 10, v[12:13]
	v_lshlrev_b32_e32 v0, 10, v0
	v_lshl_add_u64 v[12:13], v[140:141], 0, v[12:13]
	v_lshl_add_u64 v[20:21], v[140:141], 0, v[0:1]
	global_load_dwordx4 v[126:129], v[10:11], off
	global_load_dwordx4 v[110:113], v[10:11], off offset:64
	global_load_dwordx4 v[122:125], v[12:13], off
	global_load_dwordx4 v[106:109], v[12:13], off offset:64
	global_load_dwordx4 v[118:121], v[18:19], off
	global_load_dwordx4 v[102:105], v[18:19], off offset:64
	global_load_dwordx4 v[114:117], v[20:21], off
	global_load_dwordx4 v[98:101], v[20:21], off offset:64
	v_mfma_f32_16x16x32_bf16 v[10:13], v[34:37], v[134:137], 0
	s_mov_b64 s[10:11], -1
	v_mfma_f32_16x16x32_bf16 v[18:21], v[42:45], v[134:137], 0
	v_mfma_f32_16x16x32_bf16 v[146:149], v[38:41], v[6:9], v[10:13]
	v_mfma_f32_16x16x32_bf16 v[10:13], v[50:53], v[134:137], 0
	v_mfma_f32_16x16x32_bf16 v[154:157], v[46:49], v[6:9], v[18:21]
	v_mfma_f32_16x16x32_bf16 v[18:21], v[58:61], v[134:137], 0
	v_mfma_f32_16x16x32_bf16 v[130:133], v[54:57], v[6:9], v[10:13]
	v_mfma_f32_16x16x32_bf16 v[10:13], v[66:69], v[134:137], 0
	v_mfma_f32_16x16x32_bf16 v[30:33], v[62:65], v[6:9], v[18:21]
	v_mfma_f32_16x16x32_bf16 v[18:21], v[70:73], v[134:137], 0
	v_mfma_f32_16x16x32_bf16 v[22:25], v[74:77], v[6:9], v[10:13]
	v_mfma_f32_16x16x32_bf16 v[10:13], v[82:85], v[134:137], 0
	v_mfma_f32_16x16x32_bf16 v[134:137], v[86:89], v[134:137], 0
	v_mfma_f32_16x16x32_bf16 v[18:21], v[78:81], v[6:9], v[18:21]
	v_mfma_f32_16x16x32_bf16 v[10:13], v[90:93], v[6:9], v[10:13]
	v_mfma_f32_16x16x32_bf16 v[6:9], v[94:97], v[6:9], v[134:137]
	s_nop 4
	ds_read_b128 v[134:137], v197
	ds_read_b128 v[158:161], v198
	ds_read_b128 v[162:165], v199
	s_waitcnt lgkmcnt(2)
	v_add_f32_e32 v0, v146, v134
	v_mul_f32_e32 v0, 0xbfb8aa3b, v0
	v_exp_f32_e32 v0, v0
	v_add_f32_e32 v135, v147, v135
	v_mul_f32_e32 v135, 0xbfb8aa3b, v135
	v_exp_f32_e32 v135, v135
	v_add_f32_e32 v0, 1.0, v0
	v_rcp_f32_e32 v0, v0
	s_waitcnt lgkmcnt(1)
	v_add_f32_e32 v134, v154, v158
	v_add_f32_e32 v135, 1.0, v135
	v_mul_f32_e32 v134, 0xbfb8aa3b, v134
	s_waitcnt lgkmcnt(0)
	v_mul_f32_e32 v0, v162, v0
	v_exp_f32_e32 v146, v0
	v_mul_f32_e32 v144, 0x3fb17218, v0
	v_fma_f32 v145, v144, 0.5, 1.0
	v_cmp_lt_f32_e32 vcc, s72, v144
	v_mul_f32_e64 v144, v145, -v144
	v_fma_f32 v145, -v146, v146, 1.0
	v_cndmask_b32_e32 v144, v145, v144, vcc
	v_rcp_f32_e32 v145, v135
	v_add_f32_e32 v135, v155, v159
	v_mul_f32_e32 v135, 0xbfb8aa3b, v135
	v_exp_f32_e32 v134, v134
	v_mul_f32_e32 v168, v163, v145
	v_exp_f32_e32 v147, v168
	v_exp_f32_e32 v135, v135
	v_mul_f32_e32 v145, 0x3fb17218, v168
	v_fma_f32 v154, v145, 0.5, 1.0
	v_cmp_lt_f32_e32 vcc, s72, v145
	v_mul_f32_e64 v145, v154, -v145
	v_fma_f32 v154, -v147, v147, 1.0
	v_add_f32_e32 v134, 1.0, v134
	v_add_f32_e32 v135, 1.0, v135
	v_cndmask_b32_e32 v145, v154, v145, vcc
	v_rcp_f32_e32 v134, v134
	v_sqrt_f32_e32 v144, v144
	v_rcp_f32_e32 v135, v135
	v_sqrt_f32_e32 v145, v145
	s_nop 0
	v_pk_mul_f32 v[134:135], v[134:135], v[144:145]
	s_nop 0
	v_pk_mul_f32 v[150:151], v[150:151], v[134:135]
	v_add_f32_e32 v134, v148, v136
	v_mul_f32_e32 v134, 0xbfb8aa3b, v134
	v_exp_f32_e32 v134, v134
	s_nop 0
	v_add_f32_e32 v134, 1.0, v134
	v_rcp_f32_e32 v135, v134
	v_add_f32_e32 v134, v156, v160
	v_mul_f32_e32 v134, 0xbfb8aa3b, v134
	v_exp_f32_e32 v134, v134
	v_mul_f32_e32 v169, v164, v135
	v_exp_f32_e32 v144, v169
	v_mul_f32_e32 v135, 0x3fb17218, v169
	v_fma_f32 v136, v135, 0.5, 1.0
	v_cmp_lt_f32_e32 vcc, s72, v135
	v_mul_f32_e64 v135, v136, -v135
	v_fma_f32 v136, -v144, v144, 1.0
	v_cndmask_b32_e32 v135, v136, v135, vcc
	v_sqrt_f32_e32 v136, v135
	v_add_f32_e32 v135, v149, v137
	v_mul_f32_e32 v135, 0xbfb8aa3b, v135
	v_exp_f32_e32 v135, v135
	v_add_f32_e32 v134, 1.0, v134
	v_rcp_f32_e32 v134, v134
	v_add_f32_e32 v135, 1.0, v135
	v_rcp_f32_e32 v137, v135
	v_add_f32_e32 v135, v157, v161
	v_mul_f32_e32 v135, 0xbfb8aa3b, v135
	v_exp_f32_e32 v135, v135
	v_mul_f32_e32 v170, v165, v137
	v_exp_f32_e32 v145, v170
	v_mul_f32_e32 v137, 0x3fb17218, v170
	v_fma_f32 v148, v137, 0.5, 1.0
	v_cmp_lt_f32_e32 vcc, s72, v137
	v_mul_f32_e64 v137, v148, -v137
	v_fma_f32 v148, -v145, v145, 1.0
	v_add_f32_e32 v135, 1.0, v135
	v_cndmask_b32_e32 v137, v148, v137, vcc
	v_rcp_f32_e32 v135, v135
	v_sqrt_f32_e32 v137, v137
	s_nop 0
	v_pk_mul_f32 v[134:135], v[134:135], v[136:137]
	s_nop 0
	v_pk_mul_f32 v[148:149], v[152:153], v[134:135]
	ds_read_b128 v[134:137], v202
	ds_read_b128 v[152:155], v203
	ds_read_b128 v[156:159], v204
	s_waitcnt lgkmcnt(2)
	v_add_f32_e32 v130, v130, v134
	v_mul_f32_e32 v130, 0xbfb8aa3b, v130
	v_exp_f32_e32 v130, v130
	v_add_f32_e32 v131, v131, v135
	v_mul_f32_e32 v131, 0xbfb8aa3b, v131
	s_waitcnt lgkmcnt(1)
	v_add_f32_e32 v30, v30, v152
	v_exp_f32_e32 v131, v131
	v_mul_f32_e32 v30, 0xbfb8aa3b, v30
	v_add_f32_e32 v130, 1.0, v130
	v_exp_f32_e32 v30, v30
	v_add_f32_e32 v31, v31, v153
	v_rcp_f32_e32 v130, v130
	v_mul_f32_e32 v31, 0xbfb8aa3b, v31
	v_add_f32_e32 v131, 1.0, v131
	v_exp_f32_e32 v31, v31
	v_rcp_f32_e32 v131, v131
	v_add_f32_e32 v30, 1.0, v30
	v_rcp_f32_e32 v134, v30
	s_waitcnt lgkmcnt(0)
	v_mul_f32_e32 v30, v156, v130
	v_exp_f32_e32 v130, v30
	v_add_f32_e32 v31, 1.0, v31
	v_rcp_f32_e32 v135, v31
	v_mul_f32_e32 v31, v157, v131
	v_mul_f32_e32 v152, 0x3fb17218, v30
	v_exp_f32_e32 v131, v31
	v_fma_f32 v156, v152, 0.5, 1.0
	v_cmp_lt_f32_e32 vcc, s72, v152
	v_mul_f32_e64 v152, v156, -v152
	v_fma_f32 v156, -v130, v130, 1.0
	v_mul_f32_e32 v153, 0x3fb17218, v31
	v_cndmask_b32_e32 v152, v156, v152, vcc
	v_fma_f32 v156, v153, 0.5, 1.0
	v_cmp_lt_f32_e32 vcc, s72, v153
	v_mul_f32_e64 v153, v156, -v153
	v_fma_f32 v156, -v131, v131, 1.0
	v_cndmask_b32_e32 v153, v156, v153, vcc
	v_sqrt_f32_e32 v152, v152
	v_sqrt_f32_e32 v153, v153
	v_add_f32_e32 v33, v33, v155
	v_mul_f32_e32 v33, 0xbfb8aa3b, v33
	v_exp_f32_e32 v33, v33
	v_pk_mul_f32 v[134:135], v[134:135], v[152:153]
	v_add_f32_e32 v33, 1.0, v33
	v_pk_mul_f32 v[134:135], v[26:27], v[134:135]
	v_add_f32_e32 v26, v132, v136
	v_mul_f32_e32 v26, 0xbfb8aa3b, v26
	v_exp_f32_e32 v26, v26
	v_add_f32_e32 v27, v32, v154
	v_mul_f32_e32 v27, 0xbfb8aa3b, v27
	v_exp_f32_e32 v27, v27
	v_add_f32_e32 v26, 1.0, v26
	v_rcp_f32_e32 v26, v26
	v_rcp_f32_e32 v33, v33
	v_add_f32_e32 v27, 1.0, v27
	v_rcp_f32_e32 v32, v27
	v_mul_f32_e32 v26, v158, v26
	v_exp_f32_e32 v132, v26
	v_mul_f32_e32 v27, 0x3fb17218, v26
	v_fma_f32 v136, v27, 0.5, 1.0
	v_cmp_lt_f32_e32 vcc, s72, v27
	v_mul_f32_e64 v27, v136, -v27
	v_fma_f32 v136, -v132, v132, 1.0
	v_cndmask_b32_e32 v27, v136, v27, vcc
	v_sqrt_f32_e32 v136, v27
	v_add_f32_e32 v27, v133, v137
	v_mul_f32_e32 v27, 0xbfb8aa3b, v27
	v_exp_f32_e32 v27, v27
	s_nop 0
	v_add_f32_e32 v27, 1.0, v27
	v_rcp_f32_e32 v27, v27
	s_nop 0
	v_mul_f32_e32 v27, v159, v27
	v_exp_f32_e32 v133, v27
	ds_read_b128 v[154:157], v205
	ds_read_b128 v[158:161], v206
	ds_read_b128 v[162:165], v207
	v_mul_f32_e32 v137, 0x3fb17218, v27
	v_fma_f32 v152, v137, 0.5, 1.0
	v_cmp_lt_f32_e32 vcc, s72, v137
	v_mul_f32_e64 v137, v152, -v137
	v_fma_f32 v152, -v133, v133, 1.0
	s_waitcnt lgkmcnt(2)
	v_add_f32_e32 v22, v22, v154
	v_cndmask_b32_e32 v137, v152, v137, vcc
	v_mul_f32_e32 v22, 0xbfb8aa3b, v22
	v_sqrt_f32_e32 v137, v137
	v_exp_f32_e32 v22, v22
	s_waitcnt lgkmcnt(1)
	v_add_f32_e32 v18, v18, v158
	v_mul_f32_e32 v18, 0xbfb8aa3b, v18
	v_pk_mul_f32 v[32:33], v[32:33], v[136:137]
	v_add_f32_e32 v22, 1.0, v22
	v_exp_f32_e32 v18, v18
	v_pk_mul_f32 v[136:137], v[28:29], v[32:33]
	v_rcp_f32_e32 v28, v22
	v_add_f32_e32 v23, v23, v155
	v_add_f32_e32 v18, 1.0, v18
	v_rcp_f32_e32 v22, v18
	s_waitcnt lgkmcnt(0)
	v_mul_f32_e32 v18, v162, v28
	v_mul_f32_e32 v23, 0xbfb8aa3b, v23
	v_exp_f32_e32 v154, v18
	v_exp_f32_e32 v23, v23
	v_mul_f32_e32 v28, 0x3fb17218, v18
	v_add_f32_e32 v19, v19, v159
	v_fma_f32 v29, v28, 0.5, 1.0
	v_mul_f32_e32 v19, 0xbfb8aa3b, v19
	v_cmp_lt_f32_e32 vcc, s72, v28
	v_mul_f32_e64 v28, v29, -v28
	v_fma_f32 v29, -v154, v154, 1.0
	v_add_f32_e32 v23, 1.0, v23
	v_exp_f32_e32 v19, v19
	v_cndmask_b32_e32 v28, v29, v28, vcc
	v_rcp_f32_e32 v29, v23
	v_sqrt_f32_e32 v28, v28
	v_add_f32_e32 v19, 1.0, v19
	v_rcp_f32_e32 v23, v19
	v_mul_f32_e32 v19, v163, v29
	v_exp_f32_e32 v155, v19
	v_mul_f32_e32 v29, 0x3fb17218, v19
	v_fma_f32 v32, v29, 0.5, 1.0
	v_cmp_lt_f32_e32 vcc, s72, v29
	v_mul_f32_e64 v29, v32, -v29
	v_fma_f32 v32, -v155, v155, 1.0
	v_cndmask_b32_e32 v29, v32, v29, vcc
	v_sqrt_f32_e32 v29, v29
	s_nop 0
	v_pk_mul_f32 v[22:23], v[22:23], v[28:29]
	s_nop 0
	v_pk_mul_f32 v[158:159], v[14:15], v[22:23]
	v_add_f32_e32 v14, v24, v156
	v_mul_f32_e32 v14, 0xbfb8aa3b, v14
	v_exp_f32_e32 v14, v14
	s_nop 0
	v_add_f32_e32 v14, 1.0, v14
	v_rcp_f32_e32 v15, v14
	v_add_f32_e32 v14, v20, v160
	v_mul_f32_e32 v14, 0xbfb8aa3b, v14
	v_exp_f32_e32 v14, v14
	v_mul_f32_e32 v20, v164, v15
	v_exp_f32_e32 v152, v20
	v_mul_f32_e32 v15, 0x3fb17218, v20
	v_fma_f32 v22, v15, 0.5, 1.0
	v_cmp_lt_f32_e32 vcc, s72, v15
	v_mul_f32_e64 v15, v22, -v15
	v_fma_f32 v22, -v152, v152, 1.0
	v_cndmask_b32_e32 v15, v22, v15, vcc
	v_sqrt_f32_e32 v22, v15
	v_add_f32_e32 v15, v25, v157
	v_mul_f32_e32 v15, 0xbfb8aa3b, v15
	v_exp_f32_e32 v15, v15
	v_add_f32_e32 v14, 1.0, v14
	v_rcp_f32_e32 v14, v14
	v_add_f32_e32 v15, 1.0, v15
	v_rcp_f32_e32 v23, v15
	v_add_f32_e32 v15, v21, v161
	v_mul_f32_e32 v15, 0xbfb8aa3b, v15
	v_exp_f32_e32 v15, v15
	v_mul_f32_e32 v21, v165, v23
	v_exp_f32_e32 v153, v21
	v_mul_f32_e32 v23, 0x3fb17218, v21
	v_fma_f32 v24, v23, 0.5, 1.0
	v_cmp_lt_f32_e32 vcc, s72, v23
	v_mul_f32_e64 v23, v24, -v23
	v_fma_f32 v24, -v153, v153, 1.0
	v_add_f32_e32 v15, 1.0, v15
	v_cndmask_b32_e32 v23, v24, v23, vcc
	v_rcp_f32_e32 v15, v15
	v_sqrt_f32_e32 v23, v23
	s_nop 0
	v_pk_mul_f32 v[14:15], v[14:15], v[22:23]
	s_nop 0
	v_pk_mul_f32 v[156:157], v[16:17], v[14:15]
	ds_read_b128 v[14:17], v208
	ds_read_b128 v[22:25], v209
	ds_read_b128 v[162:165], v210
	s_waitcnt lgkmcnt(2)
	v_add_f32_e32 v10, v10, v14
	v_mul_f32_e32 v10, 0xbfb8aa3b, v10
	v_exp_f32_e32 v10, v10
	v_add_f32_e32 v11, v11, v15
	v_mul_f32_e32 v11, 0xbfb8aa3b, v11
	v_exp_f32_e32 v11, v11
	v_add_f32_e32 v10, 1.0, v10
	v_rcp_f32_e32 v10, v10
	s_waitcnt lgkmcnt(1)
	v_add_f32_e32 v6, v6, v22
	v_add_f32_e32 v11, 1.0, v11
	v_rcp_f32_e32 v11, v11
	s_waitcnt lgkmcnt(0)
	v_mul_f32_e32 v14, v162, v10
	v_exp_f32_e32 v160, v14
	v_add_f32_e32 v7, v7, v23
	v_mul_f32_e32 v15, v163, v11
	v_mul_f32_e32 v6, 0xbfb8aa3b, v6
	v_mul_f32_e32 v10, 0x3fb17218, v14
	v_mul_f32_e32 v7, 0xbfb8aa3b, v7
	v_exp_f32_e32 v161, v15
	v_exp_f32_e32 v6, v6
	v_fma_f32 v22, v10, 0.5, 1.0
	v_exp_f32_e32 v7, v7
	v_cmp_lt_f32_e32 vcc, s72, v10
	v_mul_f32_e64 v10, v22, -v10
	v_fma_f32 v22, -v160, v160, 1.0
	v_mul_f32_e32 v11, 0x3fb17218, v15
	v_cndmask_b32_e32 v10, v22, v10, vcc
	v_fma_f32 v22, v11, 0.5, 1.0
	v_cmp_lt_f32_e32 vcc, s72, v11
	v_mul_f32_e64 v11, v22, -v11
	v_fma_f32 v22, -v161, v161, 1.0
	v_add_f32_e32 v6, 1.0, v6
	v_add_f32_e32 v7, 1.0, v7
	v_cndmask_b32_e32 v11, v22, v11, vcc
	v_rcp_f32_e32 v6, v6
	v_sqrt_f32_e32 v10, v10
	v_rcp_f32_e32 v7, v7
	v_sqrt_f32_e32 v11, v11
	s_nop 0
	v_pk_mul_f32 v[6:7], v[6:7], v[10:11]
	s_nop 0
	v_pk_mul_f32 v[162:163], v[2:3], v[6:7]
	v_add_f32_e32 v2, v12, v16
	v_mul_f32_e32 v2, 0xbfb8aa3b, v2
	v_exp_f32_e32 v2, v2
	s_nop 0
	v_add_f32_e32 v2, 1.0, v2
	v_rcp_f32_e32 v3, v2
	v_add_f32_e32 v2, v8, v24
	v_mul_f32_e32 v2, 0xbfb8aa3b, v2
	v_exp_f32_e32 v2, v2
	v_mul_f32_e32 v8, v164, v3
	v_exp_f32_e32 v164, v8
	v_mul_f32_e32 v3, 0x3fb17218, v8
	v_fma_f32 v6, v3, 0.5, 1.0
	v_cmp_lt_f32_e32 vcc, s72, v3
	v_mul_f32_e64 v3, v6, -v3
	v_fma_f32 v6, -v164, v164, 1.0
	v_cndmask_b32_e32 v3, v6, v3, vcc
	v_sqrt_f32_e32 v6, v3
	v_add_f32_e32 v3, v13, v17
	v_mul_f32_e32 v3, 0xbfb8aa3b, v3
	v_exp_f32_e32 v3, v3
	v_add_f32_e32 v2, 1.0, v2
	v_rcp_f32_e32 v2, v2
	v_add_f32_e32 v3, 1.0, v3
	v_rcp_f32_e32 v7, v3
	v_add_f32_e32 v3, v9, v25
	v_mul_f32_e32 v3, 0xbfb8aa3b, v3
	v_exp_f32_e32 v3, v3
	v_mul_f32_e32 v9, v165, v7
	v_exp_f32_e32 v165, v9
	v_mul_f32_e32 v7, 0x3fb17218, v9
	v_fma_f32 v10, v7, 0.5, 1.0
	v_cmp_lt_f32_e32 vcc, s72, v7
	v_mul_f32_e64 v7, v10, -v7
	v_fma_f32 v10, -v165, v165, 1.0
	v_add_f32_e32 v3, 1.0, v3
	v_cndmask_b32_e32 v7, v10, v7, vcc
	v_rcp_f32_e32 v3, v3
	v_sqrt_f32_e32 v7, v7
	s_and_b64 vcc, exec, s[44:45]
	v_pk_mul_f32 v[2:3], v[2:3], v[6:7]
	s_nop 0
	v_pk_mul_f32 v[166:167], v[4:5], v[2:3]
	v_cvt_pkrtz_f16_f32 v2, v0, v150
	v_cvt_pkrtz_f16_f32 v3, v168, v151
	v_cvt_pkrtz_f16_f32 v4, v169, v148
	v_cvt_pkrtz_f16_f32 v5, v170, v149
	global_store_dwordx4 v[142:143], v[2:5], off offset:-2048
	s_nop 1
	v_cvt_pkrtz_f16_f32 v2, v30, v134
	v_cvt_pkrtz_f16_f32 v3, v31, v135
	v_cvt_pkrtz_f16_f32 v4, v26, v136
	v_cvt_pkrtz_f16_f32 v5, v27, v137
	global_store_dwordx4 v[142:143], v[2:5], off offset:-1024
	s_nop 1
	v_cvt_pkrtz_f16_f32 v2, v18, v158
	v_cvt_pkrtz_f16_f32 v3, v19, v159
	v_cvt_pkrtz_f16_f32 v4, v20, v156
	v_cvt_pkrtz_f16_f32 v5, v21, v157
	global_store_dwordx4 v[142:143], v[2:5], off
	s_nop 1
	v_cvt_pkrtz_f16_f32 v2, v14, v162
	v_cvt_pkrtz_f16_f32 v3, v15, v163
	v_cvt_pkrtz_f16_f32 v4, v8, v166
	v_cvt_pkrtz_f16_f32 v5, v9, v167
	global_store_dwordx4 v[142:143], v[2:5], off offset:1024
	s_cbranch_vccz .LBB0_341
	s_mov_b32 s10, 0x10001
	s_mov_b32 s11, 0x10001
	s_mov_b64 s[12:13], exec
	s_mov_b64 exec, s[10:11]
	v_fma_f32 v150, v172, v150, v214
	v_mul_f32_e32 v146, v146, v172
	v_fma_f32 v151, v173, v151, v215
	v_mul_f32_e32 v147, v147, v173
	v_fma_f32 v148, v174, v148, v216
	v_mul_f32_e32 v144, v144, v174
	v_fma_f32 v149, v175, v149, v217
	v_mul_f32_e32 v145, v145, v175
	v_fma_f32 v134, v176, v134, v218
	v_mul_f32_e32 v130, v130, v176
	v_fma_f32 v135, v177, v135, v219
	v_mul_f32_e32 v131, v131, v177
	v_fma_f32 v136, v178, v136, v220
	v_mul_f32_e32 v132, v132, v178
	v_fma_f32 v137, v179, v137, v221
	v_mul_f32_e32 v133, v133, v179
	v_fma_f32 v158, v180, v158, v222
	v_mul_f32_e32 v154, v154, v180
	v_fma_f32 v159, v181, v159, v223
	v_mul_f32_e32 v155, v155, v181
	v_fma_f32 v156, v182, v156, v224
	v_mul_f32_e32 v152, v152, v182
	v_fma_f32 v157, v183, v157, v225
	v_mul_f32_e32 v153, v153, v183
	v_fma_f32 v162, v192, v162, v234
	v_mul_f32_e32 v160, v160, v192
	v_fma_f32 v163, v193, v163, v235
	v_mul_f32_e32 v161, v161, v193
	v_fma_f32 v166, v194, v166, v236
	v_mul_f32_e32 v164, v164, v194
	v_fma_f32 v167, v195, v167, v237
	v_mul_f32_e32 v165, v165, v195
	s_mov_b64 exec, s[12:13]
	s_nop 4
	v_fmac_f32_dpp v150, v150, v146 row_shl:1 row_mask:0xf bank_mask:0xf bound_ctrl:1
	v_mul_f32_dpp v146, v146, v146 row_shl:1 row_mask:0xf bank_mask:0xf
	v_fmac_f32_dpp v151, v151, v147 row_shl:1 row_mask:0xf bank_mask:0xf bound_ctrl:1
	v_mul_f32_dpp v147, v147, v147 row_shl:1 row_mask:0xf bank_mask:0xf
	v_fmac_f32_dpp v148, v148, v144 row_shl:1 row_mask:0xf bank_mask:0xf bound_ctrl:1
	v_mul_f32_dpp v144, v144, v144 row_shl:1 row_mask:0xf bank_mask:0xf
	v_fmac_f32_dpp v149, v149, v145 row_shl:1 row_mask:0xf bank_mask:0xf bound_ctrl:1
	v_mul_f32_dpp v145, v145, v145 row_shl:1 row_mask:0xf bank_mask:0xf
	v_fmac_f32_dpp v134, v134, v130 row_shl:1 row_mask:0xf bank_mask:0xf bound_ctrl:1
	v_mul_f32_dpp v130, v130, v130 row_shl:1 row_mask:0xf bank_mask:0xf
	v_fmac_f32_dpp v135, v135, v131 row_shl:1 row_mask:0xf bank_mask:0xf bound_ctrl:1
	v_mul_f32_dpp v131, v131, v131 row_shl:1 row_mask:0xf bank_mask:0xf
	v_fmac_f32_dpp v136, v136, v132 row_shl:1 row_mask:0xf bank_mask:0xf bound_ctrl:1
	v_mul_f32_dpp v132, v132, v132 row_shl:1 row_mask:0xf bank_mask:0xf
	v_fmac_f32_dpp v137, v137, v133 row_shl:1 row_mask:0xf bank_mask:0xf bound_ctrl:1
	v_mul_f32_dpp v133, v133, v133 row_shl:1 row_mask:0xf bank_mask:0xf
	v_fmac_f32_dpp v158, v158, v154 row_shl:1 row_mask:0xf bank_mask:0xf bound_ctrl:1
	v_mul_f32_dpp v154, v154, v154 row_shl:1 row_mask:0xf bank_mask:0xf
	v_fmac_f32_dpp v159, v159, v155 row_shl:1 row_mask:0xf bank_mask:0xf bound_ctrl:1
	v_mul_f32_dpp v155, v155, v155 row_shl:1 row_mask:0xf bank_mask:0xf
	v_fmac_f32_dpp v156, v156, v152 row_shl:1 row_mask:0xf bank_mask:0xf bound_ctrl:1
	v_mul_f32_dpp v152, v152, v152 row_shl:1 row_mask:0xf bank_mask:0xf
	v_fmac_f32_dpp v157, v157, v153 row_shl:1 row_mask:0xf bank_mask:0xf bound_ctrl:1
	v_mul_f32_dpp v153, v153, v153 row_shl:1 row_mask:0xf bank_mask:0xf
	v_fmac_f32_dpp v162, v162, v160 row_shl:1 row_mask:0xf bank_mask:0xf bound_ctrl:1
	v_mul_f32_dpp v160, v160, v160 row_shl:1 row_mask:0xf bank_mask:0xf
	v_fmac_f32_dpp v163, v163, v161 row_shl:1 row_mask:0xf bank_mask:0xf bound_ctrl:1
	v_mul_f32_dpp v161, v161, v161 row_shl:1 row_mask:0xf bank_mask:0xf
	v_fmac_f32_dpp v166, v166, v164 row_shl:1 row_mask:0xf bank_mask:0xf bound_ctrl:1
	v_mul_f32_dpp v164, v164, v164 row_shl:1 row_mask:0xf bank_mask:0xf
	v_fmac_f32_dpp v167, v167, v165 row_shl:1 row_mask:0xf bank_mask:0xf bound_ctrl:1
	v_mul_f32_dpp v165, v165, v165 row_shl:1 row_mask:0xf bank_mask:0xf
	v_fmac_f32_dpp v150, v150, v146 row_shl:2 row_mask:0xf bank_mask:0xf bound_ctrl:1
	v_mul_f32_dpp v146, v146, v146 row_shl:2 row_mask:0xf bank_mask:0xf
	v_fmac_f32_dpp v151, v151, v147 row_shl:2 row_mask:0xf bank_mask:0xf bound_ctrl:1
	v_mul_f32_dpp v147, v147, v147 row_shl:2 row_mask:0xf bank_mask:0xf
	v_fmac_f32_dpp v148, v148, v144 row_shl:2 row_mask:0xf bank_mask:0xf bound_ctrl:1
	v_mul_f32_dpp v144, v144, v144 row_shl:2 row_mask:0xf bank_mask:0xf
	v_fmac_f32_dpp v149, v149, v145 row_shl:2 row_mask:0xf bank_mask:0xf bound_ctrl:1
	v_mul_f32_dpp v145, v145, v145 row_shl:2 row_mask:0xf bank_mask:0xf
	v_fmac_f32_dpp v134, v134, v130 row_shl:2 row_mask:0xf bank_mask:0xf bound_ctrl:1
	v_mul_f32_dpp v130, v130, v130 row_shl:2 row_mask:0xf bank_mask:0xf
	v_fmac_f32_dpp v135, v135, v131 row_shl:2 row_mask:0xf bank_mask:0xf bound_ctrl:1
	v_mul_f32_dpp v131, v131, v131 row_shl:2 row_mask:0xf bank_mask:0xf
	v_fmac_f32_dpp v136, v136, v132 row_shl:2 row_mask:0xf bank_mask:0xf bound_ctrl:1
	v_mul_f32_dpp v132, v132, v132 row_shl:2 row_mask:0xf bank_mask:0xf
	v_fmac_f32_dpp v137, v137, v133 row_shl:2 row_mask:0xf bank_mask:0xf bound_ctrl:1
	v_mul_f32_dpp v133, v133, v133 row_shl:2 row_mask:0xf bank_mask:0xf
	v_fmac_f32_dpp v158, v158, v154 row_shl:2 row_mask:0xf bank_mask:0xf bound_ctrl:1
	v_mul_f32_dpp v154, v154, v154 row_shl:2 row_mask:0xf bank_mask:0xf
	v_fmac_f32_dpp v159, v159, v155 row_shl:2 row_mask:0xf bank_mask:0xf bound_ctrl:1
	v_mul_f32_dpp v155, v155, v155 row_shl:2 row_mask:0xf bank_mask:0xf
	v_fmac_f32_dpp v156, v156, v152 row_shl:2 row_mask:0xf bank_mask:0xf bound_ctrl:1
	v_mul_f32_dpp v152, v152, v152 row_shl:2 row_mask:0xf bank_mask:0xf
	v_fmac_f32_dpp v157, v157, v153 row_shl:2 row_mask:0xf bank_mask:0xf bound_ctrl:1
	v_mul_f32_dpp v153, v153, v153 row_shl:2 row_mask:0xf bank_mask:0xf
	v_fmac_f32_dpp v162, v162, v160 row_shl:2 row_mask:0xf bank_mask:0xf bound_ctrl:1
	v_mul_f32_dpp v160, v160, v160 row_shl:2 row_mask:0xf bank_mask:0xf
	v_fmac_f32_dpp v163, v163, v161 row_shl:2 row_mask:0xf bank_mask:0xf bound_ctrl:1
	v_mul_f32_dpp v161, v161, v161 row_shl:2 row_mask:0xf bank_mask:0xf
	v_fmac_f32_dpp v166, v166, v164 row_shl:2 row_mask:0xf bank_mask:0xf bound_ctrl:1
	v_mul_f32_dpp v164, v164, v164 row_shl:2 row_mask:0xf bank_mask:0xf
	v_fmac_f32_dpp v167, v167, v165 row_shl:2 row_mask:0xf bank_mask:0xf bound_ctrl:1
	v_mul_f32_dpp v165, v165, v165 row_shl:2 row_mask:0xf bank_mask:0xf
	v_fmac_f32_dpp v150, v150, v146 row_shl:4 row_mask:0xf bank_mask:0xf bound_ctrl:1
	v_mul_f32_dpp v146, v146, v146 row_shl:4 row_mask:0xf bank_mask:0xf
	v_fmac_f32_dpp v151, v151, v147 row_shl:4 row_mask:0xf bank_mask:0xf bound_ctrl:1
	v_mul_f32_dpp v147, v147, v147 row_shl:4 row_mask:0xf bank_mask:0xf
	v_fmac_f32_dpp v148, v148, v144 row_shl:4 row_mask:0xf bank_mask:0xf bound_ctrl:1
	v_mul_f32_dpp v144, v144, v144 row_shl:4 row_mask:0xf bank_mask:0xf
	v_fmac_f32_dpp v149, v149, v145 row_shl:4 row_mask:0xf bank_mask:0xf bound_ctrl:1
	v_mul_f32_dpp v145, v145, v145 row_shl:4 row_mask:0xf bank_mask:0xf
	v_fmac_f32_dpp v134, v134, v130 row_shl:4 row_mask:0xf bank_mask:0xf bound_ctrl:1
	v_mul_f32_dpp v130, v130, v130 row_shl:4 row_mask:0xf bank_mask:0xf
	v_fmac_f32_dpp v135, v135, v131 row_shl:4 row_mask:0xf bank_mask:0xf bound_ctrl:1
	v_mul_f32_dpp v131, v131, v131 row_shl:4 row_mask:0xf bank_mask:0xf
	v_fmac_f32_dpp v136, v136, v132 row_shl:4 row_mask:0xf bank_mask:0xf bound_ctrl:1
	v_mul_f32_dpp v132, v132, v132 row_shl:4 row_mask:0xf bank_mask:0xf
	v_fmac_f32_dpp v137, v137, v133 row_shl:4 row_mask:0xf bank_mask:0xf bound_ctrl:1
	v_mul_f32_dpp v133, v133, v133 row_shl:4 row_mask:0xf bank_mask:0xf
	v_fmac_f32_dpp v158, v158, v154 row_shl:4 row_mask:0xf bank_mask:0xf bound_ctrl:1
	v_mul_f32_dpp v154, v154, v154 row_shl:4 row_mask:0xf bank_mask:0xf
	v_fmac_f32_dpp v159, v159, v155 row_shl:4 row_mask:0xf bank_mask:0xf bound_ctrl:1
	v_mul_f32_dpp v155, v155, v155 row_shl:4 row_mask:0xf bank_mask:0xf
	v_fmac_f32_dpp v156, v156, v152 row_shl:4 row_mask:0xf bank_mask:0xf bound_ctrl:1
	v_mul_f32_dpp v152, v152, v152 row_shl:4 row_mask:0xf bank_mask:0xf
	v_fmac_f32_dpp v157, v157, v153 row_shl:4 row_mask:0xf bank_mask:0xf bound_ctrl:1
	v_mul_f32_dpp v153, v153, v153 row_shl:4 row_mask:0xf bank_mask:0xf
	v_fmac_f32_dpp v162, v162, v160 row_shl:4 row_mask:0xf bank_mask:0xf bound_ctrl:1
	v_mul_f32_dpp v160, v160, v160 row_shl:4 row_mask:0xf bank_mask:0xf
	v_fmac_f32_dpp v163, v163, v161 row_shl:4 row_mask:0xf bank_mask:0xf bound_ctrl:1
	v_mul_f32_dpp v161, v161, v161 row_shl:4 row_mask:0xf bank_mask:0xf
	v_fmac_f32_dpp v166, v166, v164 row_shl:4 row_mask:0xf bank_mask:0xf bound_ctrl:1
	v_mul_f32_dpp v164, v164, v164 row_shl:4 row_mask:0xf bank_mask:0xf
	v_fmac_f32_dpp v167, v167, v165 row_shl:4 row_mask:0xf bank_mask:0xf bound_ctrl:1
	v_mul_f32_dpp v165, v165, v165 row_shl:4 row_mask:0xf bank_mask:0xf
	v_fmac_f32_dpp v150, v150, v146 row_shl:8 row_mask:0xf bank_mask:0xf bound_ctrl:1
	v_mul_f32_dpp v146, v146, v146 row_shl:8 row_mask:0xf bank_mask:0xf
	v_fmac_f32_dpp v151, v151, v147 row_shl:8 row_mask:0xf bank_mask:0xf bound_ctrl:1
	v_mul_f32_dpp v147, v147, v147 row_shl:8 row_mask:0xf bank_mask:0xf
	v_fmac_f32_dpp v148, v148, v144 row_shl:8 row_mask:0xf bank_mask:0xf bound_ctrl:1
	v_mul_f32_dpp v144, v144, v144 row_shl:8 row_mask:0xf bank_mask:0xf
	v_fmac_f32_dpp v149, v149, v145 row_shl:8 row_mask:0xf bank_mask:0xf bound_ctrl:1
	v_mul_f32_dpp v145, v145, v145 row_shl:8 row_mask:0xf bank_mask:0xf
	v_fmac_f32_dpp v134, v134, v130 row_shl:8 row_mask:0xf bank_mask:0xf bound_ctrl:1
	v_mul_f32_dpp v130, v130, v130 row_shl:8 row_mask:0xf bank_mask:0xf
	v_fmac_f32_dpp v135, v135, v131 row_shl:8 row_mask:0xf bank_mask:0xf bound_ctrl:1
	v_mul_f32_dpp v131, v131, v131 row_shl:8 row_mask:0xf bank_mask:0xf
	v_fmac_f32_dpp v136, v136, v132 row_shl:8 row_mask:0xf bank_mask:0xf bound_ctrl:1
	v_mul_f32_dpp v132, v132, v132 row_shl:8 row_mask:0xf bank_mask:0xf
	v_fmac_f32_dpp v137, v137, v133 row_shl:8 row_mask:0xf bank_mask:0xf bound_ctrl:1
	v_mul_f32_dpp v133, v133, v133 row_shl:8 row_mask:0xf bank_mask:0xf
	v_fmac_f32_dpp v158, v158, v154 row_shl:8 row_mask:0xf bank_mask:0xf bound_ctrl:1
	v_mul_f32_dpp v154, v154, v154 row_shl:8 row_mask:0xf bank_mask:0xf
	v_fmac_f32_dpp v159, v159, v155 row_shl:8 row_mask:0xf bank_mask:0xf bound_ctrl:1
	v_mul_f32_dpp v155, v155, v155 row_shl:8 row_mask:0xf bank_mask:0xf
	v_fmac_f32_dpp v156, v156, v152 row_shl:8 row_mask:0xf bank_mask:0xf bound_ctrl:1
	v_mul_f32_dpp v152, v152, v152 row_shl:8 row_mask:0xf bank_mask:0xf
	v_fmac_f32_dpp v157, v157, v153 row_shl:8 row_mask:0xf bank_mask:0xf bound_ctrl:1
	v_mul_f32_dpp v153, v153, v153 row_shl:8 row_mask:0xf bank_mask:0xf
	v_fmac_f32_dpp v162, v162, v160 row_shl:8 row_mask:0xf bank_mask:0xf bound_ctrl:1
	v_mul_f32_dpp v160, v160, v160 row_shl:8 row_mask:0xf bank_mask:0xf
	v_fmac_f32_dpp v163, v163, v161 row_shl:8 row_mask:0xf bank_mask:0xf bound_ctrl:1
	v_mul_f32_dpp v161, v161, v161 row_shl:8 row_mask:0xf bank_mask:0xf
	v_fmac_f32_dpp v166, v166, v164 row_shl:8 row_mask:0xf bank_mask:0xf bound_ctrl:1
	v_mul_f32_dpp v164, v164, v164 row_shl:8 row_mask:0xf bank_mask:0xf
	v_fmac_f32_dpp v167, v167, v165 row_shl:8 row_mask:0xf bank_mask:0xf bound_ctrl:1
	v_mul_f32_dpp v165, v165, v165 row_shl:8 row_mask:0xf bank_mask:0xf
	v_mov_b64_e32 v[172:173], v[146:147]
	v_mov_b64_e32 v[214:215], v[150:151]
	v_mov_b64_e32 v[174:175], v[144:145]
	v_mov_b64_e32 v[216:217], v[148:149]
	v_mov_b64_e32 v[176:177], v[130:131]
	v_mov_b64_e32 v[218:219], v[134:135]
	v_mov_b64_e32 v[178:179], v[132:133]
	v_mov_b64_e32 v[220:221], v[136:137]
	v_mov_b64_e32 v[180:181], v[154:155]
	v_mov_b64_e32 v[222:223], v[158:159]
	v_mov_b64_e32 v[182:183], v[152:153]
	v_mov_b64_e32 v[224:225], v[156:157]
	v_mov_b64_e32 v[192:193], v[160:161]
	v_mov_b64_e32 v[234:235], v[162:163]
	v_mov_b64_e32 v[194:195], v[164:165]
	v_mov_b64_e32 v[236:237], v[166:167]
	s_mov_b64 s[10:11], 0
.LBB0_341:
	s_andn2_b64 vcc, exec, s[10:11]
	s_cbranch_vccnz .LBB0_338
	v_fmac_f32_dpp v150, v214, v146 row_shl:15 row_mask:0xf bank_mask:0xf bound_ctrl:1
	v_mul_f32_dpp v146, v172, v146 row_shl:15 row_mask:0xf bank_mask:0xf
	v_fmac_f32_dpp v151, v215, v147 row_shl:15 row_mask:0xf bank_mask:0xf bound_ctrl:1
	v_mul_f32_dpp v147, v173, v147 row_shl:15 row_mask:0xf bank_mask:0xf
	v_fmac_f32_dpp v148, v216, v144 row_shl:15 row_mask:0xf bank_mask:0xf bound_ctrl:1
	v_mul_f32_dpp v144, v174, v144 row_shl:15 row_mask:0xf bank_mask:0xf
	v_fmac_f32_dpp v149, v217, v145 row_shl:15 row_mask:0xf bank_mask:0xf bound_ctrl:1
	v_mul_f32_dpp v145, v175, v145 row_shl:15 row_mask:0xf bank_mask:0xf
	v_fmac_f32_dpp v134, v218, v130 row_shl:15 row_mask:0xf bank_mask:0xf bound_ctrl:1
	v_mul_f32_dpp v130, v176, v130 row_shl:15 row_mask:0xf bank_mask:0xf
	v_fmac_f32_dpp v135, v219, v131 row_shl:15 row_mask:0xf bank_mask:0xf bound_ctrl:1
	v_mul_f32_dpp v131, v177, v131 row_shl:15 row_mask:0xf bank_mask:0xf
	v_fmac_f32_dpp v136, v220, v132 row_shl:15 row_mask:0xf bank_mask:0xf bound_ctrl:1
	v_mul_f32_dpp v132, v178, v132 row_shl:15 row_mask:0xf bank_mask:0xf
	v_fmac_f32_dpp v137, v221, v133 row_shl:15 row_mask:0xf bank_mask:0xf bound_ctrl:1
	v_mul_f32_dpp v133, v179, v133 row_shl:15 row_mask:0xf bank_mask:0xf
	v_fmac_f32_dpp v158, v222, v154 row_shl:15 row_mask:0xf bank_mask:0xf bound_ctrl:1
	v_mul_f32_dpp v154, v180, v154 row_shl:15 row_mask:0xf bank_mask:0xf
	v_fmac_f32_dpp v159, v223, v155 row_shl:15 row_mask:0xf bank_mask:0xf bound_ctrl:1
	v_mul_f32_dpp v155, v181, v155 row_shl:15 row_mask:0xf bank_mask:0xf
	v_fmac_f32_dpp v156, v224, v152 row_shl:15 row_mask:0xf bank_mask:0xf bound_ctrl:1
	v_mul_f32_dpp v152, v182, v152 row_shl:15 row_mask:0xf bank_mask:0xf
	v_fmac_f32_dpp v157, v225, v153 row_shl:15 row_mask:0xf bank_mask:0xf bound_ctrl:1
	v_mul_f32_dpp v153, v183, v153 row_shl:15 row_mask:0xf bank_mask:0xf
	v_fmac_f32_dpp v162, v234, v160 row_shl:15 row_mask:0xf bank_mask:0xf bound_ctrl:1
	v_mul_f32_dpp v160, v192, v160 row_shl:15 row_mask:0xf bank_mask:0xf
	v_fmac_f32_dpp v163, v235, v161 row_shl:15 row_mask:0xf bank_mask:0xf bound_ctrl:1
	v_mul_f32_dpp v161, v193, v161 row_shl:15 row_mask:0xf bank_mask:0xf
	v_fmac_f32_dpp v166, v236, v164 row_shl:15 row_mask:0xf bank_mask:0xf bound_ctrl:1
	v_mul_f32_dpp v164, v194, v164 row_shl:15 row_mask:0xf bank_mask:0xf
	v_fmac_f32_dpp v167, v237, v165 row_shl:15 row_mask:0xf bank_mask:0xf bound_ctrl:1
	v_mul_f32_dpp v165, v195, v165 row_shl:15 row_mask:0xf bank_mask:0xf
	v_fmac_f32_dpp v150, v150, v146 row_shr:1 row_mask:0xf bank_mask:0xf bound_ctrl:1
	v_mul_f32_dpp v146, v146, v146 row_shr:1 row_mask:0xf bank_mask:0xf
	v_fmac_f32_dpp v151, v151, v147 row_shr:1 row_mask:0xf bank_mask:0xf bound_ctrl:1
	v_mul_f32_dpp v147, v147, v147 row_shr:1 row_mask:0xf bank_mask:0xf
	v_fmac_f32_dpp v148, v148, v144 row_shr:1 row_mask:0xf bank_mask:0xf bound_ctrl:1
	v_mul_f32_dpp v144, v144, v144 row_shr:1 row_mask:0xf bank_mask:0xf
	v_fmac_f32_dpp v149, v149, v145 row_shr:1 row_mask:0xf bank_mask:0xf bound_ctrl:1
	v_mul_f32_dpp v145, v145, v145 row_shr:1 row_mask:0xf bank_mask:0xf
	v_fmac_f32_dpp v134, v134, v130 row_shr:1 row_mask:0xf bank_mask:0xf bound_ctrl:1
	v_mul_f32_dpp v130, v130, v130 row_shr:1 row_mask:0xf bank_mask:0xf
	v_fmac_f32_dpp v135, v135, v131 row_shr:1 row_mask:0xf bank_mask:0xf bound_ctrl:1
	v_mul_f32_dpp v131, v131, v131 row_shr:1 row_mask:0xf bank_mask:0xf
	v_fmac_f32_dpp v136, v136, v132 row_shr:1 row_mask:0xf bank_mask:0xf bound_ctrl:1
	v_mul_f32_dpp v132, v132, v132 row_shr:1 row_mask:0xf bank_mask:0xf
	v_fmac_f32_dpp v137, v137, v133 row_shr:1 row_mask:0xf bank_mask:0xf bound_ctrl:1
	v_mul_f32_dpp v133, v133, v133 row_shr:1 row_mask:0xf bank_mask:0xf
	v_fmac_f32_dpp v158, v158, v154 row_shr:1 row_mask:0xf bank_mask:0xf bound_ctrl:1
	v_mul_f32_dpp v154, v154, v154 row_shr:1 row_mask:0xf bank_mask:0xf
	v_fmac_f32_dpp v159, v159, v155 row_shr:1 row_mask:0xf bank_mask:0xf bound_ctrl:1
	v_mul_f32_dpp v155, v155, v155 row_shr:1 row_mask:0xf bank_mask:0xf
	v_fmac_f32_dpp v156, v156, v152 row_shr:1 row_mask:0xf bank_mask:0xf bound_ctrl:1
	v_mul_f32_dpp v152, v152, v152 row_shr:1 row_mask:0xf bank_mask:0xf
	v_fmac_f32_dpp v157, v157, v153 row_shr:1 row_mask:0xf bank_mask:0xf bound_ctrl:1
	v_mul_f32_dpp v153, v153, v153 row_shr:1 row_mask:0xf bank_mask:0xf
	v_fmac_f32_dpp v162, v162, v160 row_shr:1 row_mask:0xf bank_mask:0xf bound_ctrl:1
	v_mul_f32_dpp v160, v160, v160 row_shr:1 row_mask:0xf bank_mask:0xf
	v_fmac_f32_dpp v163, v163, v161 row_shr:1 row_mask:0xf bank_mask:0xf bound_ctrl:1
	v_mul_f32_dpp v161, v161, v161 row_shr:1 row_mask:0xf bank_mask:0xf
	v_fmac_f32_dpp v166, v166, v164 row_shr:1 row_mask:0xf bank_mask:0xf bound_ctrl:1
	v_mul_f32_dpp v164, v164, v164 row_shr:1 row_mask:0xf bank_mask:0xf
	v_fmac_f32_dpp v167, v167, v165 row_shr:1 row_mask:0xf bank_mask:0xf bound_ctrl:1
	v_mul_f32_dpp v165, v165, v165 row_shr:1 row_mask:0xf bank_mask:0xf
	v_fmac_f32_dpp v150, v150, v146 row_shr:2 row_mask:0xf bank_mask:0xf bound_ctrl:1
	v_mul_f32_dpp v146, v146, v146 row_shr:2 row_mask:0xf bank_mask:0xf
	v_fmac_f32_dpp v151, v151, v147 row_shr:2 row_mask:0xf bank_mask:0xf bound_ctrl:1
	v_mul_f32_dpp v147, v147, v147 row_shr:2 row_mask:0xf bank_mask:0xf
	v_fmac_f32_dpp v148, v148, v144 row_shr:2 row_mask:0xf bank_mask:0xf bound_ctrl:1
	v_mul_f32_dpp v144, v144, v144 row_shr:2 row_mask:0xf bank_mask:0xf
	v_fmac_f32_dpp v149, v149, v145 row_shr:2 row_mask:0xf bank_mask:0xf bound_ctrl:1
	v_mul_f32_dpp v145, v145, v145 row_shr:2 row_mask:0xf bank_mask:0xf
	v_fmac_f32_dpp v134, v134, v130 row_shr:2 row_mask:0xf bank_mask:0xf bound_ctrl:1
	v_mul_f32_dpp v130, v130, v130 row_shr:2 row_mask:0xf bank_mask:0xf
	v_fmac_f32_dpp v135, v135, v131 row_shr:2 row_mask:0xf bank_mask:0xf bound_ctrl:1
	v_mul_f32_dpp v131, v131, v131 row_shr:2 row_mask:0xf bank_mask:0xf
	v_fmac_f32_dpp v136, v136, v132 row_shr:2 row_mask:0xf bank_mask:0xf bound_ctrl:1
	v_mul_f32_dpp v132, v132, v132 row_shr:2 row_mask:0xf bank_mask:0xf
	v_fmac_f32_dpp v137, v137, v133 row_shr:2 row_mask:0xf bank_mask:0xf bound_ctrl:1
	v_mul_f32_dpp v133, v133, v133 row_shr:2 row_mask:0xf bank_mask:0xf
	v_fmac_f32_dpp v158, v158, v154 row_shr:2 row_mask:0xf bank_mask:0xf bound_ctrl:1
	v_mul_f32_dpp v154, v154, v154 row_shr:2 row_mask:0xf bank_mask:0xf
	v_fmac_f32_dpp v159, v159, v155 row_shr:2 row_mask:0xf bank_mask:0xf bound_ctrl:1
	v_mul_f32_dpp v155, v155, v155 row_shr:2 row_mask:0xf bank_mask:0xf
	v_fmac_f32_dpp v156, v156, v152 row_shr:2 row_mask:0xf bank_mask:0xf bound_ctrl:1
	v_mul_f32_dpp v152, v152, v152 row_shr:2 row_mask:0xf bank_mask:0xf
	v_fmac_f32_dpp v157, v157, v153 row_shr:2 row_mask:0xf bank_mask:0xf bound_ctrl:1
	v_mul_f32_dpp v153, v153, v153 row_shr:2 row_mask:0xf bank_mask:0xf
	v_fmac_f32_dpp v162, v162, v160 row_shr:2 row_mask:0xf bank_mask:0xf bound_ctrl:1
	v_mul_f32_dpp v160, v160, v160 row_shr:2 row_mask:0xf bank_mask:0xf
	v_fmac_f32_dpp v163, v163, v161 row_shr:2 row_mask:0xf bank_mask:0xf bound_ctrl:1
	v_mul_f32_dpp v161, v161, v161 row_shr:2 row_mask:0xf bank_mask:0xf
	v_fmac_f32_dpp v166, v166, v164 row_shr:2 row_mask:0xf bank_mask:0xf bound_ctrl:1
	v_mul_f32_dpp v164, v164, v164 row_shr:2 row_mask:0xf bank_mask:0xf
	v_fmac_f32_dpp v167, v167, v165 row_shr:2 row_mask:0xf bank_mask:0xf bound_ctrl:1
	v_mul_f32_dpp v165, v165, v165 row_shr:2 row_mask:0xf bank_mask:0xf
	v_fmac_f32_dpp v150, v150, v146 row_shr:4 row_mask:0xf bank_mask:0xf bound_ctrl:1
	v_mul_f32_dpp v146, v146, v146 row_shr:4 row_mask:0xf bank_mask:0xf
	v_fmac_f32_dpp v151, v151, v147 row_shr:4 row_mask:0xf bank_mask:0xf bound_ctrl:1
	v_mul_f32_dpp v147, v147, v147 row_shr:4 row_mask:0xf bank_mask:0xf
	v_fmac_f32_dpp v148, v148, v144 row_shr:4 row_mask:0xf bank_mask:0xf bound_ctrl:1
	v_mul_f32_dpp v144, v144, v144 row_shr:4 row_mask:0xf bank_mask:0xf
	v_fmac_f32_dpp v149, v149, v145 row_shr:4 row_mask:0xf bank_mask:0xf bound_ctrl:1
	v_mul_f32_dpp v145, v145, v145 row_shr:4 row_mask:0xf bank_mask:0xf
	v_fmac_f32_dpp v134, v134, v130 row_shr:4 row_mask:0xf bank_mask:0xf bound_ctrl:1
	v_mul_f32_dpp v130, v130, v130 row_shr:4 row_mask:0xf bank_mask:0xf
	v_fmac_f32_dpp v135, v135, v131 row_shr:4 row_mask:0xf bank_mask:0xf bound_ctrl:1
	v_mul_f32_dpp v131, v131, v131 row_shr:4 row_mask:0xf bank_mask:0xf
	v_fmac_f32_dpp v136, v136, v132 row_shr:4 row_mask:0xf bank_mask:0xf bound_ctrl:1
	v_mul_f32_dpp v132, v132, v132 row_shr:4 row_mask:0xf bank_mask:0xf
	v_fmac_f32_dpp v137, v137, v133 row_shr:4 row_mask:0xf bank_mask:0xf bound_ctrl:1
	v_mul_f32_dpp v133, v133, v133 row_shr:4 row_mask:0xf bank_mask:0xf
	v_fmac_f32_dpp v158, v158, v154 row_shr:4 row_mask:0xf bank_mask:0xf bound_ctrl:1
	v_mul_f32_dpp v154, v154, v154 row_shr:4 row_mask:0xf bank_mask:0xf
	v_fmac_f32_dpp v159, v159, v155 row_shr:4 row_mask:0xf bank_mask:0xf bound_ctrl:1
	v_mul_f32_dpp v155, v155, v155 row_shr:4 row_mask:0xf bank_mask:0xf
	v_fmac_f32_dpp v156, v156, v152 row_shr:4 row_mask:0xf bank_mask:0xf bound_ctrl:1
	v_mul_f32_dpp v152, v152, v152 row_shr:4 row_mask:0xf bank_mask:0xf
	v_fmac_f32_dpp v157, v157, v153 row_shr:4 row_mask:0xf bank_mask:0xf bound_ctrl:1
	v_mul_f32_dpp v153, v153, v153 row_shr:4 row_mask:0xf bank_mask:0xf
	v_fmac_f32_dpp v162, v162, v160 row_shr:4 row_mask:0xf bank_mask:0xf bound_ctrl:1
	v_mul_f32_dpp v160, v160, v160 row_shr:4 row_mask:0xf bank_mask:0xf
	v_fmac_f32_dpp v163, v163, v161 row_shr:4 row_mask:0xf bank_mask:0xf bound_ctrl:1
	v_mul_f32_dpp v161, v161, v161 row_shr:4 row_mask:0xf bank_mask:0xf
	v_fmac_f32_dpp v166, v166, v164 row_shr:4 row_mask:0xf bank_mask:0xf bound_ctrl:1
	v_mul_f32_dpp v164, v164, v164 row_shr:4 row_mask:0xf bank_mask:0xf
	v_fmac_f32_dpp v167, v167, v165 row_shr:4 row_mask:0xf bank_mask:0xf bound_ctrl:1
	v_mul_f32_dpp v165, v165, v165 row_shr:4 row_mask:0xf bank_mask:0xf
	v_fmac_f32_dpp v150, v150, v146 row_shr:8 row_mask:0xf bank_mask:0xf bound_ctrl:1
	v_mul_f32_dpp v146, v146, v146 row_shr:8 row_mask:0xf bank_mask:0xf
	v_fmac_f32_dpp v151, v151, v147 row_shr:8 row_mask:0xf bank_mask:0xf bound_ctrl:1
	v_mul_f32_dpp v147, v147, v147 row_shr:8 row_mask:0xf bank_mask:0xf
	v_fmac_f32_dpp v148, v148, v144 row_shr:8 row_mask:0xf bank_mask:0xf bound_ctrl:1
	v_mul_f32_dpp v144, v144, v144 row_shr:8 row_mask:0xf bank_mask:0xf
	v_fmac_f32_dpp v149, v149, v145 row_shr:8 row_mask:0xf bank_mask:0xf bound_ctrl:1
	v_mul_f32_dpp v145, v145, v145 row_shr:8 row_mask:0xf bank_mask:0xf
	v_fmac_f32_dpp v134, v134, v130 row_shr:8 row_mask:0xf bank_mask:0xf bound_ctrl:1
	v_mul_f32_dpp v130, v130, v130 row_shr:8 row_mask:0xf bank_mask:0xf
	v_fmac_f32_dpp v135, v135, v131 row_shr:8 row_mask:0xf bank_mask:0xf bound_ctrl:1
	v_mul_f32_dpp v131, v131, v131 row_shr:8 row_mask:0xf bank_mask:0xf
	v_fmac_f32_dpp v136, v136, v132 row_shr:8 row_mask:0xf bank_mask:0xf bound_ctrl:1
	v_mul_f32_dpp v132, v132, v132 row_shr:8 row_mask:0xf bank_mask:0xf
	v_fmac_f32_dpp v137, v137, v133 row_shr:8 row_mask:0xf bank_mask:0xf bound_ctrl:1
	v_mul_f32_dpp v133, v133, v133 row_shr:8 row_mask:0xf bank_mask:0xf
	v_fmac_f32_dpp v158, v158, v154 row_shr:8 row_mask:0xf bank_mask:0xf bound_ctrl:1
	v_mul_f32_dpp v154, v154, v154 row_shr:8 row_mask:0xf bank_mask:0xf
	v_fmac_f32_dpp v159, v159, v155 row_shr:8 row_mask:0xf bank_mask:0xf bound_ctrl:1
	v_mul_f32_dpp v155, v155, v155 row_shr:8 row_mask:0xf bank_mask:0xf
	v_fmac_f32_dpp v156, v156, v152 row_shr:8 row_mask:0xf bank_mask:0xf bound_ctrl:1
	v_mul_f32_dpp v152, v152, v152 row_shr:8 row_mask:0xf bank_mask:0xf
	v_fmac_f32_dpp v157, v157, v153 row_shr:8 row_mask:0xf bank_mask:0xf bound_ctrl:1
	v_mul_f32_dpp v153, v153, v153 row_shr:8 row_mask:0xf bank_mask:0xf
	v_fmac_f32_dpp v162, v162, v160 row_shr:8 row_mask:0xf bank_mask:0xf bound_ctrl:1
	v_mul_f32_dpp v160, v160, v160 row_shr:8 row_mask:0xf bank_mask:0xf
	v_fmac_f32_dpp v163, v163, v161 row_shr:8 row_mask:0xf bank_mask:0xf bound_ctrl:1
	v_mul_f32_dpp v161, v161, v161 row_shr:8 row_mask:0xf bank_mask:0xf
	v_fmac_f32_dpp v166, v166, v164 row_shr:8 row_mask:0xf bank_mask:0xf bound_ctrl:1
	v_mul_f32_dpp v164, v164, v164 row_shr:8 row_mask:0xf bank_mask:0xf
	v_fmac_f32_dpp v167, v167, v165 row_shr:8 row_mask:0xf bank_mask:0xf bound_ctrl:1
	v_mul_f32_dpp v165, v165, v165 row_shr:8 row_mask:0xf bank_mask:0xf
	v_mov_b64_e32 v[172:173], v[146:147]
	v_mov_b64_e32 v[214:215], v[150:151]
	v_mov_b64_e32 v[174:175], v[144:145]
	v_mov_b64_e32 v[216:217], v[148:149]
	v_mov_b64_e32 v[176:177], v[130:131]
	v_mov_b64_e32 v[218:219], v[134:135]
	v_mov_b64_e32 v[178:179], v[132:133]
	v_mov_b64_e32 v[220:221], v[136:137]
	v_mov_b64_e32 v[180:181], v[154:155]
	v_mov_b64_e32 v[222:223], v[158:159]
	v_mov_b64_e32 v[182:183], v[152:153]
	v_mov_b64_e32 v[224:225], v[156:157]
	v_mov_b64_e32 v[192:193], v[160:161]
	v_mov_b64_e32 v[234:235], v[162:163]
	v_mov_b64_e32 v[194:195], v[164:165]
	v_mov_b64_e32 v[236:237], v[166:167]
	s_branch .LBB0_338
.LBB0_343:
	s_cmp_eq_u32 s43, 0
	s_cselect_b32 s3, 15, 0
	v_cmp_eq_u32_e32 vcc, s3, v184
	s_and_saveexec_b64 s[8:9], vcc
	s_cbranch_execz .LBB0_345
	s_lshl_b32 s3, s74, 1
	s_or_b32 s3, s3, s43
	s_mulk_i32 s3, 0x44
	s_ashr_i32 s11, s59, 31
	s_add_u32 s10, s3, s59
	s_addc_u32 s11, 0, s11
	s_lshl_b64 s[10:11], s[10:11], 9
	s_add_u32 s10, s10, s18
	s_addc_u32 s11, s11, s19
	v_lshl_add_u64 v[2:3], s[10:11], 0, v[138:139]
	v_lshlrev_b64 v[6:7], 2, v[2:3]
	v_lshl_add_u64 v[22:23], s[22:23], 0, v[6:7]
	v_lshl_add_u64 v[24:25], s[20:21], 0, v[6:7]
	global_store_dwordx4 v[22:23], v[172:175], off
	global_store_dwordx4 v[24:25], v[214:217], off
	global_store_dwordx4 v[22:23], v[176:179], off offset:64
	global_store_dwordx4 v[24:25], v[218:221], off offset:64
	global_store_dwordx4 v[22:23], v[180:183], off offset:128
	global_store_dwordx4 v[24:25], v[222:225], off offset:128
	global_store_dwordx4 v[22:23], v[192:195], off offset:192
	global_store_dwordx4 v[24:25], v[234:237], off offset:192
